# a3 tail gain vectors hoisted out of loop; final+norm row loads issued up front with counted waits (on top of band edits)
# speedup vs baseline: 1.0206x; 1.0169x over previous
; #define LAS __attribute__((address_space(3)))
; __device__ __forceinline__ void a3_load(A3Regs& R, const Params& P, int item, int tid) {
;     const int cidx = item / 6, h = item % 6; const bf16_t* proj = (const bf16_t*)(P.ws + WS_PROJ);
; #pragma unroll
;     for (int u = 0; u < 2; ++u) { const int i = tid + 512 * u; const size_t o = (size_t)(cidx * 64 + (i >> 4)) * 128 + (i & 15) * 8;
;         R.z[u] = *(const u32x4*)(pjp(proj, AF, 128, h, 0) + o); R.q[u] = *(const u32x4*)(pjp(proj, AQ, 128, h, 0) + o); R.v[u] = *(const u32x4*)(pjp(proj, AI, 128, h, 0) + o); R.g[u] = *(const u32x4*)(pjp(proj, AG, 128, h, 0) + o); }
;     const bf16_t* st = (const bf16_t*)(P.ws + WS_STA) + (size_t)(cidx * 6 + h) * 16384;
; #pragma unroll
;     for (int u = 0; u < 4; ++u) R.st[u] = *(const u32x4*)(st + (size_t)(tid + 512 * u) * 8);
; }
; __device__ __forceinline__ void a3_phase(const Params& P, int layer, LAS unsigned char* lds, int tid) {
;     const int w = tid >> 6, lane = tid & 63, kp = tid & 63, G = gridDim.x;
;     LAS float* part = (LAS float*)(lds + R_AUX);
;     A3Regs R; int it = blockIdx.x; if (it < 3072) a3_load(R, P, it, tid);
.LBB0_103:
	s_andn2_b64 vcc, exec, s[0:1]
	v_ashrrev_i32_e32 v151, 31, v150
	v_and_b32_e32 v103, 0xffffff00, v150
	s_cbranch_vccnz .LBB0_119
	v_readlane_b32 s52, v247, 14
	s_lshl_b64 s[0:1], s[36:37], 2
	v_readlane_b32 s60, v247, 22
	v_readlane_b32 s61, v247, 23
	s_add_u32 s10, s60, s0
	s_addc_u32 s11, s61, s1
	s_add_u32 s12, s4, 0xcc00000
	s_addc_u32 s13, s5, 0
	s_add_u32 s8, s4, 0xfc00000
	s_addc_u32 s9, s5, 0
	s_lshl_b64 s[0:1], s[90:91], 1
	v_readlane_b32 s53, v247, 15
	v_readlane_b32 s54, v247, 16
	v_readlane_b32 s55, v247, 17
	v_readlane_b32 s56, v247, 18
	v_readlane_b32 s57, v247, 19
	v_readlane_b32 s58, v247, 20
	v_readlane_b32 s59, v247, 21
	v_readlane_b32 s62, v247, 24
	v_readlane_b32 s63, v247, 25
	v_readlane_b32 s64, v247, 26
	v_readlane_b32 s65, v247, 27
	v_readlane_b32 s66, v247, 28
	v_readlane_b32 s67, v247, 29
	v_writelane_b32 v247, s8, 53
	s_add_u32 s8, s8, s0
	v_writelane_b32 v247, s9, 54
	s_addc_u32 s9, s9, s1
	v_writelane_b32 v247, s12, 55
	s_add_u32 s12, s12, s0
	v_writelane_b32 v247, s13, 56
	s_addc_u32 s13, s13, s1
	s_add_u32 s14, s4, 0x12c00000
	s_addc_u32 s15, s5, 0
	v_writelane_b32 v247, s14, 57
	s_add_u32 s14, s14, s0
	v_add_u32_e32 v60, 0x200, v150
	v_writelane_b32 v247, s15, 58
	s_addc_u32 s15, s15, s1
	v_ashrrev_i32_e32 v102, 4, v150
	v_ashrrev_i32_e32 v104, 4, v60
	v_lshlrev_b32_e32 v66, 3, v150
	s_add_u32 s18, s4, 0x15c00000
	s_waitcnt vmcnt(0)
	v_add_u32_e32 v0, s88, v102
	v_add_u32_e32 v16, s88, v104
	v_and_b32_e32 v48, 0x78, v66
	s_addc_u32 s19, s5, 0
	v_ashrrev_i32_e32 v1, 31, v0
	v_ashrrev_i32_e32 v17, 31, v16
	s_add_u32 s0, s18, s0
	v_lshlrev_b64 v[8:9], 8, v[0:1]
	v_lshlrev_b32_e32 v18, 1, v48
	v_lshlrev_b64 v[24:25], 8, v[16:17]
	s_addc_u32 s1, s19, s1
	v_or_b32_e32 v8, v8, v18
	v_or_b32_e32 v24, v24, v18
	v_lshl_add_u64 v[12:13], s[0:1], 0, v[8:9]
	v_lshl_add_u64 v[28:29], s[0:1], 0, v[24:25]
	v_readlane_b32 s0, v248, 18
	v_readlane_b32 s1, v248, 19
	s_add_u32 s0, s4, s0
	s_addc_u32 s1, s5, s1
	v_add_u32_e32 v62, 0x400, v150
	v_add_u32_e32 v64, 0x600, v150
	s_add_u32 s0, s0, 0x2ac00000
	v_ashrrev_i32_e32 v61, 31, v60
	v_ashrrev_i32_e32 v63, 31, v62
	v_ashrrev_i32_e32 v65, 31, v64
	s_addc_u32 s1, s1, 0
	v_lshlrev_b64 v[52:53], 4, v[150:151]
	v_lshlrev_b64 v[50:51], 4, v[60:61]
	v_lshlrev_b64 v[54:55], 4, v[62:63]
	v_lshlrev_b64 v[56:57], 4, v[64:65]
	v_lshl_add_u64 v[0:1], s[8:9], 0, v[8:9]
	v_lshl_add_u64 v[4:5], s[12:13], 0, v[8:9]
	v_lshl_add_u64 v[10:11], s[14:15], 0, v[8:9]
	v_lshl_add_u64 v[16:17], s[8:9], 0, v[24:25]
	v_lshl_add_u64 v[20:21], s[12:13], 0, v[24:25]
	v_lshl_add_u64 v[26:27], s[14:15], 0, v[24:25]
	v_lshl_add_u64 v[32:33], s[0:1], 0, v[52:53]
	v_lshl_add_u64 v[36:37], s[0:1], 0, v[50:51]
	v_lshl_add_u64 v[40:41], s[0:1], 0, v[54:55]
	v_lshl_add_u64 v[44:45], s[0:1], 0, v[56:57]
	global_load_dwordx4 v[0:3], v[0:1], off
	s_nop 0
	global_load_dwordx4 v[4:7], v[4:5], off
	s_nop 0
	global_load_dwordx4 v[8:11], v[10:11], off
	s_nop 0
	global_load_dwordx4 v[12:15], v[12:13], off
	s_nop 0
	global_load_dwordx4 v[16:19], v[16:17], off
	s_nop 0
	global_load_dwordx4 v[20:23], v[20:21], off
	s_nop 0
	global_load_dwordx4 v[24:27], v[26:27], off
	s_nop 0
	global_load_dwordx4 v[28:31], v[28:29], off
	s_nop 0
	global_load_dwordx4 v[32:35], v[32:33], off
	s_nop 0
	global_load_dwordx4 v[36:39], v[36:37], off
	s_nop 0
	global_load_dwordx4 v[40:43], v[40:41], off
	s_nop 0
	global_load_dwordx4 v[44:47], v[44:45], off
	v_and_b32_e32 v58, 63, v150
	v_lshlrev_b32_e32 v65, 2, v58
	v_and_b32_e32 v61, 15, v150
	v_add_u32_e32 v67, 0, v65
	v_bfe_u32 v72, v150, 4, 2
	v_and_b32_e32 v65, 12, v65
	v_bfe_u32 v74, v150, 2, 2
	v_lshlrev_b32_e32 v73, 8, v61
	v_bitop3_b32 v75, v65, v72, v74 bitop3:0x36
	v_lshl_or_b32 v108, v75, 4, v73
	v_or_b32_e32 v75, 4, v72
	v_bitop3_b32 v75, v65, v75, v74 bitop3:0x36
	v_lshl_or_b32 v109, v75, 4, v73
	v_or_b32_e32 v75, 8, v72
	v_bitop3_b32 v75, v65, v75, v74 bitop3:0x36
	v_lshl_or_b32 v110, v75, 4, v73
	v_or_b32_e32 v75, 12, v72
	v_ashrrev_i32_e32 v49, 6, v150
	v_bitop3_b32 v65, v65, v75, v74 bitop3:0x36
	v_lshl_or_b32 v111, v65, 4, v73
	v_and_b32_e32 v65, 0x7fffffc, v49
	v_or_b32_e32 v76, 1, v65
	v_bfe_u32 v73, v150, 1, 1
	v_lshlrev_b32_e32 v74, 6, v150
	v_and_or_b32 v75, v150, 12, v72
	v_and_b32_e32 v66, 8, v66
	v_lshlrev_b32_e32 v77, 1, v76
	v_or_b32_e32 v78, 2, v65
	v_or_b32_e32 v80, 3, v65
	v_and_or_b32 v66, v74, s92, v66
	v_lshlrev_b32_e32 v74, 1, v65
	v_bitop3_b32 v77, v77, v75, v73 bitop3:0x36
	v_lshlrev_b32_e32 v79, 1, v78
	v_lshlrev_b32_e32 v81, 1, v80
	v_and_b32_e32 v71, 3, v49
	v_bitop3_b32 v74, v74, v75, v73 bitop3:0x36
	v_bitop3_b32 v79, v79, v75, v73 bitop3:0x36
	v_bitop3_b32 v73, v81, v75, v73 bitop3:0x36
	v_lshl_add_u32 v75, v77, 4, 0
	v_lshlrev_b32_e32 v77, 2, v72
	v_lshl_add_u32 v112, v71, 12, 0
	v_lshl_add_u32 v92, v79, 4, 0
	v_lshl_or_b32 v71, v71, 4, v61
	v_or_b32_e32 v79, 2, v77
	v_cmp_gt_u32_e64 s[50:51], v79, v71
	v_or_b32_e32 v79, 3, v77
	v_cmp_gt_u32_e64 s[52:53], v79, v71
	v_or_b32_e32 v79, 16, v77
	v_writelane_b32 v247, s18, 59
	v_cmp_gt_u32_e64 s[54:55], v79, v71
	v_or_b32_e32 v79, 17, v77
	v_writelane_b32 v247, s19, 60
	v_cmp_gt_u32_e64 s[56:57], v79, v71
	v_or_b32_e32 v79, 18, v77
	v_writelane_b32 v247, s94, 61
	s_add_i32 s8, s94, 4
	s_mov_b32 s0, s84
	v_cmp_gt_u32_e64 s[58:59], v79, v71
	v_or_b32_e32 v79, 19, v77
	s_cmp_gt_u32 s8, 10
	v_writelane_b32 v247, s0, 62
	v_cmp_gt_u32_e64 s[60:61], v79, v71
	v_or_b32_e32 v79, 32, v77
	s_cselect_b64 s[18:19], -1, 0
	v_writelane_b32 v247, s1, 63
	s_lshl_b32 s0, s84, 7
	v_cmp_gt_u32_e64 s[62:63], v79, v71
	v_or_b32_e32 v79, 33, v77
	s_ashr_i32 s1, s0, 31
	v_cmp_gt_u32_e64 s[64:65], v79, v71
	v_or_b32_e32 v79, 34, v77
; __device__ __forceinline__ unsigned row_addr(int lane, int s) { return off_b((unsigned)(lane & 15), (unsigned)(4 * s + (lane >> 4))); }
; __device__ __forceinline__ f32x4 mfma16(bf16x8 a, bf16x8 b, f32x4 c) { return __builtin_amdgcn_mfma_f32_16x16x32_bf16(a, b, c, 0, 0, 0); }
; template <int DK, bool ISC> ...
;     ...
;     const int tb = w & 3, vh = w >> 2, g = lane >> 4, c15 = lane & 15, t = 16 * tb + c15;
;     unsigned ra[KS];
; #pragma unroll
;     for (int kk = 0; kk < KS; ++kk) ra[kk] = row_addr(lane, kk);
;     bf16x8 qf[KS], qif[KS];
; #pragma unroll
;     for (int kk = 0; kk < KS; ++kk) qf[kk] = row_frag_a(qs, ra[kk], tb);
;     f32x4 accs[4];
; #pragma unroll
;     for (int sb = 0; sb < 4; ++sb) accs[sb] = (f32x4){0.f, 0.f, 0.f, 0.f};
;     {   bf16x8 kf[2][4];
; #pragma unroll
;         for (int sb = 0; sb < 4; ++sb) kf[0][sb] = row_frag_a(ks, ra[0], sb);
; #pragma unroll
;         for (int kk = 0; kk < KS; ++kk) {
;             if (kk + 1 < KS) {
; #pragma unroll
;                 for (int sb = 0; sb < 4; ++sb) kf[(kk + 1) & 1][sb] = row_frag_a(ks, ra[kk + 1 < KS ? kk + 1 : 0], sb); }
; #pragma unroll
;             for (int sb = 0; sb < 4; ++sb) accs[sb] = mfma16(kf[kk & 1][sb], qf[kk], accs[sb]); } }
; #pragma unroll
;     for (int kk = 0; kk < KS; ++kk) qif[kk] = row_frag_a(qi, ra[kk], tb);
;     unsigned va[4];
; #pragma unroll
;     for (int i = 0; i < 4; ++i) va[i] = tr_addr<true>(lane, vh * 4 + i);
;     constexpr int NS = 2 + KS;
;     bf16x8 fa[2][4];
; #pragma unroll
;     for (int i = 0; i < 4; ++i) fa[0][i] = tr_frag_a<true>(vt, va[i], 0);
; #pragma unroll
;     for (int sb = 0; sb < 4; ++sb)
; #pragma unroll
;         for (int r = 0; r < 4; ++r) { const int s = 16 * sb + 4 * g + r; float v = accs[sb][r];
;             if (ISC) v *= exp2f(gl2 * (float)(t - s));
;             accs[sb][r] = (s <= t) ? v : 0.f; }
	v_or_b32_e32 v81, 49, v77
	v_and_b32_e32 v83, 64, v184
	s_cmp_lt_u32 s8, 11
	v_cmp_gt_u32_e64 s[66:67], v79, v71
	v_or_b32_e32 v79, 35, v77
	v_cmp_gt_u32_e64 s[8:9], v81, v71
	v_or_b32_e32 v81, 50, v77
	v_xor_b32_e32 v82, 16, v184
	v_add_u32_e32 v83, 64, v83
	v_readlane_b32 s14, v247, 6
	v_lshlrev_b32_e32 v105, 1, v58
	v_lshl_add_u32 v106, v58, 3, s74
	s_cselect_b32 s12, s93, 0x33984000
	v_cmp_gt_u32_e64 s[68:69], v79, v71
	v_or_b32_e32 v79, 48, v77
	v_cmp_gt_u32_e64 s[72:73], v81, v71
	v_or_b32_e32 v81, 51, v77
	v_cmp_lt_i32_e32 vcc, v82, v83
	v_cmp_gt_u32_e64 s[78:79], 16, v58
	v_lshl_add_u32 v121, v71, 2, s14
	v_lshlrev_b32_e32 v58, 8, v71
	s_add_i32 s14, 0, 0x18000
	v_lshlrev_b32_e32 v72, 3, v72
	v_cmp_gt_u32_e64 s[46:47], v77, v71
	v_cmp_lt_u32_e64 s[48:49], v77, v71
	v_cmp_gt_u32_e64 s[70:71], v79, v71
	v_cmp_gt_u32_e64 s[76:77], v81, v71
	v_cndmask_b32_e32 v82, v184, v82, vcc
	v_add3_u32 v72, s14, v58, v72
	v_lshlrev_b32_e32 v58, 11, v71
	v_lshlrev_b32_e32 v71, 4, v150
	v_lshlrev_b32_e32 v119, 2, v82
	v_xor_b32_e32 v82, 32, v184
	v_lshlrev_b32_e32 v95, 5, v80
	v_and_b32_e32 v80, 0xffffff00, v71
	v_lshlrev_b32_e32 v60, 4, v60
	v_and_b32_e32 v81, -4, v49
	v_cmp_lt_i32_e32 vcc, v82, v83
	v_add_u32_e32 v96, 0, v80
	v_add_u32_e32 v99, s14, v80
	v_and_b32_e32 v80, 0xffffff00, v60
	v_ashrrev_i32_e32 v62, 4, v62
	v_lshlrev_b32_e32 v114, 12, v81
	v_cndmask_b32_e32 v82, v184, v82, vcc
	v_lshlrev_b32_e32 v93, 5, v76
	v_lshl_or_b32 v76, v81, 4, v77
	v_lshlrev_b32_e32 v81, 2, v102
	v_add_u32_e32 v100, 0, v80
	v_add_u32_e32 v136, s14, v80
	v_lshlrev_b32_e32 v80, 2, v62
	v_lshlrev_b32_e32 v120, 2, v82
	v_and_b32_e32 v81, 12, v81
	v_bfe_u32 v82, v102, 2, 2
	v_lshlrev_b32_e32 v156, 8, v62
	v_and_b32_e32 v80, 12, v80
	v_bfe_u32 v62, v62, 2, 2
	v_ashrrev_i32_e32 v64, 4, v64
	v_bitop3_b32 v81, v81, v61, v82 bitop3:0x36
	v_lshlrev_b32_e32 v82, 2, v104
	v_bitop3_b32 v62, v80, v61, v62 bitop3:0x36
	v_lshlrev_b32_e32 v80, 2, v64
	v_lshlrev_b32_e32 v68, 3, v49
	v_and_b32_e32 v82, 12, v82
	v_bfe_u32 v83, v104, 2, 2
	v_lshlrev_b32_e32 v157, 8, v64
	v_and_b32_e32 v80, 12, v80
	v_bfe_u32 v64, v64, 2, 2
	s_add_i32 s13, 0, 0x10000
	v_bitop3_b32 v82, v82, v61, v83 bitop3:0x36
	v_bitop3_b32 v61, v80, v61, v64 bitop3:0x36
	v_lshlrev_b32_e32 v64, 1, v49
	v_or_b32_e32 v83, 4, v68
	s_lshl_b64 s[0:1], s[0:1], 2
	v_bfe_u32 v69, v150, 2, 4
	v_lshlrev_b32_e32 v81, 4, v81
	v_lshlrev_b32_e32 v82, 4, v82
	v_and_b32_e32 v80, 2, v64
	v_lshlrev_b32_e32 v84, 8, v83
	v_lshrrev_b32_e32 v83, 2, v83
	s_add_u32 s0, s10, s0
	v_lshlrev_b32_e32 v94, 5, v78
	v_lshl_or_b32 v78, v49, 4, v79
	v_add_u32_e32 v98, 0, v81
	v_add_u32_e32 v127, 0, v82
	v_add_u32_e32 v153, s13, v81
	v_add_u32_e32 v154, s13, v82
	v_bitop3_b32 v81, v80, v69, 4 bitop3:0x36
	v_bitop3_b32 v82, v80, v69, 8 bitop3:0x36
	v_bitop3_b32 v80, v80, v69, 12 bitop3:0x36
	v_bitop3_b32 v83, v83, v69, 3 bitop3:0x6c
	s_addc_u32 s1, s11, s1
	v_lshlrev_b32_e32 v63, 11, v49
	v_ashrrev_i32_e32 v77, 31, v76
	v_ashrrev_i32_e32 v79, 31, v78
	v_lshlrev_b32_e32 v81, 4, v81
	v_lshlrev_b32_e32 v82, 4, v82
	v_lshlrev_b32_e32 v80, 4, v80
	v_lshlrev_b32_e32 v83, 4, v83
	s_add_u32 s38, s4, s12
	v_add3_u32 v161, 0, v81, v63
	v_add3_u32 v162, 0, v82, v63
	v_add3_u32 v163, 0, v80, v63
	v_add3_u32 v164, 0, v83, v84
	v_or_b32_e32 v85, 5, v68
	v_or_b32_e32 v87, 6, v68
	v_or_b32_e32 v68, 7, v68
	v_or_b32_e32 v192, v83, v84
	v_or_b32_e32 v193, v80, v63
	v_or_b32_e32 v194, v82, v63
	v_or_b32_e32 v195, v81, v63
	s_addc_u32 s28, s5, 0
	v_lshl_add_u64 v[80:81], v[76:77], 2, s[0:1]
	v_lshl_add_u64 v[82:83], v[78:79], 2, s[0:1]
	v_readlane_b32 s0, v248, 45
	v_lshlrev_b32_e32 v86, 8, v85
	v_bfe_u32 v85, v85, 2, 2
	v_lshlrev_b32_e32 v88, 8, v87
	v_bfe_u32 v87, v87, 2, 2
	v_lshlrev_b32_e32 v89, 8, v68
	v_bfe_u32 v68, v68, 2, 2
	s_add_u32 s12, s0, s36
	v_readlane_b32 s0, v248, 46
	v_add_u32_e32 v113, s13, v108
	v_add_u32_e32 v116, s13, v109
	v_add_u32_e32 v117, s13, v110
	v_add_u32_e32 v118, s13, v111
	v_lshl_add_u32 v62, v62, 4, s13
	v_lshl_add_u32 v61, v61, 4, s13
	v_bitop3_b32 v85, v85, v69, 4 bitop3:0x36
	v_bitop3_b32 v87, v87, v69, 8 bitop3:0x36
	v_bitop3_b32 v68, v68, v69, 12 bitop3:0x36
	s_addc_u32 s13, s0, s37
	v_readlane_b32 s0, v248, 59
	v_lshlrev_b32_e32 v85, 4, v85
	v_lshlrev_b32_e32 v87, 4, v87
	v_lshlrev_b32_e32 v68, 4, v68
	s_mov_b64 s[10:11], 0x2ac00000
	v_readlane_b32 s1, v248, 60
	v_lshlrev_b32_e32 v59, 2, v150
	v_bitop3_b32 v64, v64, v69, 2 bitop3:0x6c
	v_add3_u32 v165, 0, v85, v86
	v_add3_u32 v166, 0, v87, v88
	v_add3_u32 v69, 0, v68, v89
	v_or_b32_e32 v68, v68, v89
	v_or_b32_e32 v190, v87, v88
	v_or_b32_e32 v191, v85, v86
	v_lshl_add_u64 v[84:85], v[52:53], 0, s[10:11]
	v_lshl_add_u64 v[86:87], v[50:51], 0, s[10:11]
	v_lshl_add_u64 v[88:89], v[54:55], 0, s[10:11]
	v_lshl_add_u64 v[90:91], v[56:57], 0, s[10:11]
	s_mov_b32 s11, s0
	v_cmp_gt_i32_e64 s[0:1], 7, v49
	v_and_b32_e32 v70, 12, v59
	v_lshlrev_b32_e32 v64, 4, v64
	v_writelane_b32 v246, s0, 0
	v_add_u32_e32 v59, 0, v70
	v_lshl_add_u32 v74, v74, 4, 0
	v_lshl_add_u32 v73, v73, 4, 0
	v_lshlrev_b32_e32 v65, 5, v65
	v_and_b32_e32 v71, 0xf0, v71
	v_lshlrev_b32_e32 v97, 8, v102
	v_and_b32_e32 v60, 0xf0, v60
	v_lshlrev_b32_e32 v101, 8, v104
	v_add3_u32 v160, 0, v64, v63
	v_or_b32_e32 v64, v64, v63
	v_writelane_b32 v246, s1, 1
	v_cmp_gt_i32_e64 s[0:1], 8, v49
	v_lshl_add_u32 v107, v49, 9, v106
	v_cmp_gt_i32_e64 s[40:41], 4, v49
	v_lshl_or_b32 v115, v49, 12, v183
	v_add_u32_e32 v122, v121, v103
	v_cmp_gt_i32_e64 s[2:3], 1, v49
	v_cmp_gt_i32_e64 s[80:81], 0, v49
	v_add_u32_e32 v123, v96, v71
	v_add_u32_e32 v124, v98, v97
	v_add_u32_e32 v125, v99, v71
	v_add_u32_e32 v126, v100, v60
; __device__ __forceinline__ unsigned row_addr(int lane, int s) { return off_b((unsigned)(lane & 15), (unsigned)(4 * s + (lane >> 4))); }
; __device__ __forceinline__ f32x4 mfma16(bf16x8 a, bf16x8 b, f32x4 c) { return __builtin_amdgcn_mfma_f32_16x16x32_bf16(a, b, c, 0, 0, 0); }
; template <int DK, bool ISC> ...
;     ...
;     const int tb = w & 3, vh = w >> 2, g = lane >> 4, c15 = lane & 15, t = 16 * tb + c15;
;     unsigned ra[KS];
; #pragma unroll
;     for (int kk = 0; kk < KS; ++kk) ra[kk] = row_addr(lane, kk);
;     bf16x8 qf[KS], qif[KS];
; #pragma unroll
;     for (int kk = 0; kk < KS; ++kk) qf[kk] = row_frag_a(qs, ra[kk], tb);
;     f32x4 accs[4];
; #pragma unroll
;     for (int sb = 0; sb < 4; ++sb) accs[sb] = (f32x4){0.f, 0.f, 0.f, 0.f};
;     {   bf16x8 kf[2][4];
; #pragma unroll
;         for (int sb = 0; sb < 4; ++sb) kf[0][sb] = row_frag_a(ks, ra[0], sb);
; #pragma unroll
;         for (int kk = 0; kk < KS; ++kk) {
;             if (kk + 1 < KS) {
; #pragma unroll
;                 for (int sb = 0; sb < 4; ++sb) kf[(kk + 1) & 1][sb] = row_frag_a(ks, ra[kk + 1 < KS ? kk + 1 : 0], sb); }
; #pragma unroll
;             for (int sb = 0; sb < 4; ++sb) accs[sb] = mfma16(kf[kk & 1][sb], qf[kk], accs[sb]); } }
; #pragma unroll
;     for (int kk = 0; kk < KS; ++kk) qif[kk] = row_frag_a(qi, ra[kk], tb);
;     unsigned va[4];
; #pragma unroll
;     for (int i = 0; i < 4; ++i) va[i] = tr_addr<true>(lane, vh * 4 + i);
;     constexpr int NS = 2 + KS;
;     bf16x8 fa[2][4];
; #pragma unroll
;     for (int i = 0; i < 4; ++i) fa[0][i] = tr_frag_a<true>(vt, va[i], 0);
; #pragma unroll
;     for (int sb = 0; sb < 4; ++sb)
; #pragma unroll
;         for (int r = 0; r < 4; ++r) { const int s = 16 * sb + 4 * g + r; float v = accs[sb][r];
;             if (ISC) v *= exp2f(gl2 * (float)(t - s));
;             accs[sb][r] = (s <= t) ? v : 0.f; }
;     ...
;         f32x4 gn = (f32x4){1.f, 1.f, 1.f, 1.f}; if (!ISC) gn = *(const f32x4*)(gain + v0);
	v_add_u32_e32 v127, v127, v101
	v_add_u32_e32 v152, v136, v60
	v_add_u32_e32 v153, v153, v97
	v_add_u32_e32 v154, v154, v101
	v_add_u32_e32 v156, v62, v156
	v_add_u32_e32 v157, v61, v157
	v_lshlrev_b32_e32 v158, 1, v48
	v_add_u32_e32 v159, v67, v63
	v_add_u32_e32 v160, v160, v70
	v_add_u32_e32 v161, v161, v70
	v_add_u32_e32 v162, v162, v70
	v_add_u32_e32 v163, v163, v70
	v_add_u32_e32 v164, v164, v70
	v_add_u32_e32 v165, v165, v70
	v_add_u32_e32 v166, v166, v70
	v_add_u32_e32 v167, v69, v70
	v_add_u32_e32 v168, v74, v66
	v_add_u32_e32 v169, v75, v66
	v_add_u32_e32 v170, v92, v66
	v_add_u32_e32 v171, v73, v66
	v_add_u32_e32 v172, v72, v65
	v_add_u32_e32 v173, v72, v93
	v_add_u32_e32 v174, v72, v94
	v_add_u32_e32 v175, v72, v95
	v_lshlrev_b32_e32 v136, 1, v58
	v_add_u32_e32 v189, v59, v68
	v_add_u32_e32 v190, v59, v190
	v_add_u32_e32 v191, v59, v191
	v_add_u32_e32 v192, v59, v192
	v_add_u32_e32 v193, v59, v193
	v_add_u32_e32 v194, v59, v194
	v_add_u32_e32 v195, v59, v195
	v_add_u32_e32 v196, v59, v64
	s_mov_b32 s10, s89
	v_cmp_gt_i32_e64 s[82:83], 2, v49
	v_cmp_lt_i32_e64 s[86:87], 0, v49
	v_cmp_gt_i32_e64 s[84:85], 3, v49
	v_cmp_lt_i32_e64 s[92:93], 1, v49
	v_cmp_gt_i32_e64 s[88:89], 5, v49
	v_cmp_gt_i32_e64 s[90:91], 6, v49
	v_writelane_b32 v246, s0, 2
	s_nop 1
	v_writelane_b32 v246, s1, 3
	global_load_dwordx4 v[222:225], v[80:81], off
	global_load_dwordx4 v[226:229], v[80:81], off offset:64
	global_load_dwordx4 v[236:239], v[80:81], off offset:128
	global_load_dwordx4 v[240:243], v[82:83], off
	s_branch .LBB0_106
; #define LAS __attribute__((address_space(3)))
; __device__ __forceinline__ unsigned cvt_pk_bf16(float lo, float hi) { const f32x2 f = {lo, hi}; const bf16x2_t v = __builtin_convertvector(f, bf16x2_t); return __builtin_bit_cast(unsigned, v); }
; __device__ __forceinline__ float bflo(unsigned u) { return __uint_as_float(u << 16); }
; __device__ __forceinline__ float bfhi(unsigned u) { return __uint_as_float(u & 0xffff0000u); }
; __device__ __forceinline__ float silu_f(float v) { return v * rcp_f(1.f + __expf(-v)); }
; template <int DK, bool ISC> ...
;     ...
;     u32x2 gtv[4];
; #pragma unroll
;     for (int i = 0; i < 4; ++i) gtv[i] = *(const LAS u32x2*)(gate + t * 256 + 2 * (16 * (vh * 4 + i) + 4 * g));
;     __syncthreads();
;     const float rinv = rsqrtf((red[t] + red[64 + t]) * (1.f / 128.f) + EPSN);
; #pragma unroll
;     for (int i = 0; i < 4; ++i) { const int v0 = 16 * (vh * 4 + i) + 4 * g;
;         const u32x2 gt2 = gtv[i];
;         f32x4 gn = (f32x4){1.f, 1.f, 1.f, 1.f}; if (!ISC) gn = *(const f32x4*)(gain + v0);
;         const float o0 = acco[i][0] * rinv * gn[0] * silu_f(bflo(gt2.x)), o1 = acco[i][1] * rinv * gn[1] * silu_f(bfhi(gt2.x));
;         const float o2 = acco[i][2] * rinv * gn[2] * silu_f(bflo(gt2.y)), o3 = acco[i][3] * rinv * gn[3] * silu_f(bfhi(gt2.y));
;         u32x2 o; o.x = cvt_pk_bf16(o0, o1); o.y = cvt_pk_bf16(o2, o3);
;         *(u32x2*)(y + (size_t)t * DM + v0) = o; }
.LBB0_105:
	s_or_b64 exec, exec, vcc
	ds_read_b64 v[74:75], v172
	ds_read_b64 v[72:73], v173
	ds_read_b64 v[70:71], v174
	ds_read_b64 v[66:67], v175
	s_waitcnt lgkmcnt(0)
	s_barrier
	s_lshl_b32 s42, s15, 6
	ds_read2st64_b32 v[64:65], v121 offset1:1
	s_ashr_i32 s43, s42, 31
	s_lshl_b64 s[42:43], s[42:43], 12
	s_add_u32 s42, s38, s42
	s_addc_u32 s43, s28, s43
	s_ashr_i32 s15, s14, 31
	s_lshl_b64 s[14:15], s[14:15], 1
	s_waitcnt lgkmcnt(0)
	v_add_f32_e32 v64, v64, v65
	s_add_u32 s14, s42, s14
	v_fmamk_f32 v64, v64, 0x3c000000, v181
	s_mov_b32 s42, 0x800000
	v_cmp_gt_f32_e32 vcc, s42, v64
	v_mul_f32_e32 v65, 0x4b800000, v64
	v_lshlrev_b32_e32 v96, 16, v74
	v_cndmask_b32_e32 v64, v64, v65, vcc
	v_rsq_f32_e32 v64, v64
	v_mul_f32_e32 v69, 0xbfb8aa3b, v96
	v_exp_f32_e32 v69, v69
	v_and_b32_e32 v97, 0xffff0000, v74
	v_mul_f32_e32 v65, 0x45800000, v64
	v_cndmask_b32_e32 v68, v64, v65, vcc
	v_add_f32_e32 v69, 1.0, v69
	v_rcp_f32_e32 v98, v69
	v_pk_mul_f32 v[60:61], v[60:61], v[68:69] op_sel_hi:[1,0]
	v_mul_f32_e32 v69, 0xbfb8aa3b, v97
	v_exp_f32_e32 v69, v69
	v_lshlrev_b32_e32 v74, 16, v75
	v_and_b32_e32 v75, 0xffff0000, v75
	s_addc_u32 s15, s43, s15
	v_add_f32_e32 v69, 1.0, v69
	v_rcp_f32_e32 v99, v69
	v_mul_f32_e32 v69, 0xbfb8aa3b, v74
	v_exp_f32_e32 v69, v69
	v_lshl_add_u64 v[64:65], s[14:15], 0, v[136:137]
	v_readlane_b32 s14, v248, 36
	s_add_i32 s10, s10, s14
	v_add_f32_e32 v69, 1.0, v69
	v_pk_mul_f32 v[62:63], v[62:63], v[68:69] op_sel_hi:[1,0]
	v_readlane_b32 s14, v248, 47
	v_readlane_b32 s15, v248, 48
	s_add_u32 s12, s12, s14
	s_addc_u32 s13, s13, s15
	s_andn2_b64 vcc, exec, s[0:1]
	v_pk_mul_f32 v[60:61], v[222:223], v[60:61]
	v_pk_mul_f32 v[92:93], v[98:99], v[96:97]
	v_pk_mul_f32 v[62:63], v[224:225], v[62:63]
	v_pk_mul_f32 v[60:61], v[92:93], v[60:61]
	v_rcp_f32_e32 v92, v69
	v_mul_f32_e32 v69, 0xbfb8aa3b, v75
	v_exp_f32_e32 v69, v69
	s_nop 0
	v_add_f32_e32 v69, 1.0, v69
	v_rcp_f32_e32 v93, v69
	s_nop 0
	v_pk_mul_f32 v[74:75], v[92:93], v[74:75]
	s_nop 0
	v_pk_mul_f32 v[62:63], v[74:75], v[62:63]
	v_cvt_pk_bf16_f32 v74, v60, v61
	v_cvt_pk_bf16_f32 v75, v62, v63
	v_lshl_add_u64 v[60:61], v[76:77], 1, v[64:65]
	global_store_dwordx2 v[60:61], v[74:75], off
	v_lshlrev_b32_e32 v62, 16, v72
	v_mul_f32_e32 v69, 0xbfb8aa3b, v62
	v_exp_f32_e32 v69, v69
	v_and_b32_e32 v63, 0xffff0000, v72
	v_add_f32_e32 v69, 1.0, v69
	v_rcp_f32_e32 v74, v69
	v_pk_mul_f32 v[56:57], v[56:57], v[68:69] op_sel_hi:[1,0]
	v_mul_f32_e32 v69, 0xbfb8aa3b, v63
	v_exp_f32_e32 v69, v69
	v_pk_mul_f32 v[56:57], v[226:227], v[56:57]
	v_add_f32_e32 v69, 1.0, v69
	v_rcp_f32_e32 v75, v69
	s_nop 0
	v_pk_mul_f32 v[62:63], v[74:75], v[62:63]
	s_nop 0
	v_pk_mul_f32 v[56:57], v[62:63], v[56:57]
	v_lshlrev_b32_e32 v62, 16, v73
	v_mul_f32_e32 v69, 0xbfb8aa3b, v62
	v_exp_f32_e32 v69, v69
	v_and_b32_e32 v63, 0xffff0000, v73
	v_cvt_pk_bf16_f32 v56, v56, v57
	v_add_f32_e32 v69, 1.0, v69
	v_rcp_f32_e32 v72, v69
	v_pk_mul_f32 v[58:59], v[58:59], v[68:69] op_sel_hi:[1,0]
	v_mul_f32_e32 v69, 0xbfb8aa3b, v63
	v_exp_f32_e32 v69, v69
	v_pk_mul_f32 v[58:59], v[228:229], v[58:59]
	v_add_f32_e32 v69, 1.0, v69
	v_rcp_f32_e32 v73, v69
	s_nop 0
	v_pk_mul_f32 v[62:63], v[72:73], v[62:63]
	s_nop 0
	v_pk_mul_f32 v[58:59], v[62:63], v[58:59]
	v_lshlrev_b32_e32 v62, 16, v70
	v_cvt_pk_bf16_f32 v57, v58, v59
	global_store_dwordx2 v[60:61], v[56:57], off offset:32
	v_mul_f32_e32 v69, 0xbfb8aa3b, v62
	v_exp_f32_e32 v69, v69
	v_and_b32_e32 v63, 0xffff0000, v70
	v_add_f32_e32 v69, 1.0, v69
	v_pk_mul_f32 v[52:53], v[52:53], v[68:69] op_sel_hi:[1,0]
	v_rcp_f32_e32 v72, v69
	v_pk_mul_f32 v[54:55], v[54:55], v[68:69] op_sel_hi:[1,0]
	v_pk_mul_f32 v[48:49], v[48:49], v[68:69] op_sel_hi:[1,0]
	v_pk_mul_f32 v[50:51], v[50:51], v[68:69] op_sel_hi:[1,0]
	v_pk_mul_f32 v[52:53], v[236:237], v[52:53]
	v_mul_f32_e32 v56, 0xbfb8aa3b, v63
	v_exp_f32_e32 v56, v56
	v_pk_mul_f32 v[54:55], v[238:239], v[54:55]
	v_add_f32_e32 v56, 1.0, v56
	v_rcp_f32_e32 v73, v56
	s_nop 0
	v_pk_mul_f32 v[56:57], v[72:73], v[62:63]
	s_nop 0
	v_pk_mul_f32 v[52:53], v[56:57], v[52:53]
	v_lshlrev_b32_e32 v56, 16, v71
	v_and_b32_e32 v57, 0xffff0000, v71
	v_mul_f32_e32 v62, 0xbfb8aa3b, v56
	v_mul_f32_e32 v58, 0xbfb8aa3b, v57
	v_exp_f32_e32 v62, v62
	v_exp_f32_e32 v58, v58
	v_cvt_pk_bf16_f32 v52, v52, v53
	v_add_f32_e32 v62, 1.0, v62
	v_add_f32_e32 v58, 1.0, v58
	v_rcp_f32_e32 v62, v62
	v_rcp_f32_e32 v63, v58
	s_nop 0
	v_pk_mul_f32 v[56:57], v[62:63], v[56:57]
	s_nop 0
	v_pk_mul_f32 v[54:55], v[56:57], v[54:55]
	v_lshlrev_b32_e32 v56, 16, v66
	v_cvt_pk_bf16_f32 v53, v54, v55
	global_store_dwordx2 v[60:61], v[52:53], off offset:64
	v_and_b32_e32 v57, 0xffff0000, v66
	v_mul_f32_e32 v58, 0xbfb8aa3b, v56
	v_exp_f32_e32 v58, v58
	v_pk_mul_f32 v[48:49], v[240:241], v[48:49]
	v_mul_f32_e32 v52, 0xbfb8aa3b, v57
	v_exp_f32_e32 v52, v52
	v_add_f32_e32 v58, 1.0, v58
	v_rcp_f32_e32 v58, v58
	v_pk_mul_f32 v[50:51], v[242:243], v[50:51]
	v_add_f32_e32 v52, 1.0, v52
	v_rcp_f32_e32 v59, v52
	s_nop 0
	v_pk_mul_f32 v[52:53], v[58:59], v[56:57]
	s_nop 0
	v_pk_mul_f32 v[48:49], v[52:53], v[48:49]
	v_lshlrev_b32_e32 v52, 16, v67
	v_and_b32_e32 v53, 0xffff0000, v67
	v_mul_f32_e32 v56, 0xbfb8aa3b, v52
	v_mul_f32_e32 v54, 0xbfb8aa3b, v53
	v_exp_f32_e32 v56, v56
	v_exp_f32_e32 v54, v54
	v_cvt_pk_bf16_f32 v48, v48, v49
	v_add_f32_e32 v56, 1.0, v56
	v_add_f32_e32 v54, 1.0, v54
	v_rcp_f32_e32 v56, v56
	v_rcp_f32_e32 v57, v54
	s_nop 0
	v_pk_mul_f32 v[52:53], v[56:57], v[52:53]
	s_nop 0
	v_pk_mul_f32 v[50:51], v[52:53], v[50:51]
	s_nop 0
	v_cvt_pk_bf16_f32 v49, v50, v51
	v_lshl_add_u64 v[50:51], v[78:79], 1, v[64:65]
	global_store_dwordx2 v[50:51], v[48:49], off
	s_cbranch_vccz .LBB0_118

; __device__ __forceinline__ unsigned cvt_pk_bf16(float lo, float hi) { const f32x2 f = {lo, hi}; const bf16x2_t v = __builtin_convertvector(f, bf16x2_t); return __builtin_bit_cast(unsigned, v); }
; __device__ __forceinline__ float bflo(unsigned u) { return __uint_as_float(u << 16); }
; __device__ __forceinline__ float bfhi(unsigned u) { return __uint_as_float(u & 0xffff0000u); }
; __device__ __forceinline__ float rcp_f(float v) { return __builtin_amdgcn_rcpf(v); }
; __device__ __forceinline__ float silu_f(float v) { return v * rcp_f(1.f + __expf(-v)); }
; __device__ __forceinline__ void b_item(const Params& P, int layer, LAS unsigned char* lds, int item, int tid) {
;     ...
;     __syncthreads();
;     ...
; #pragma unroll
;     for (int u = 0; u < 2; ++u) {
;         float l = lrun[u]; l += __shfl_xor(l, 16); l += __shfl_xor(l, 32);
;         const float inv = rcp_f(l);
;         const size_t tok = tok0 + 64 * qc + 32 * th + 16 * u + c15;
;         const bf16_t* gate = pjp(proj, BG, 128, h, tok);
;         bf16_t* y = (bf16_t*)(P.ws + (layer == 0 ? WS_H : WS_D1)) + tok * DM + YB + h * 128;
; #pragma unroll
;         for (int vb = 0; vb < 8; ++vb) { const int v0 = 16 * vb + 4 * g; const u32x2 gt2 = *(const u32x2*)(gate + v0);
;             u32x2 o; o.x = cvt_pk_bf16(acco[u][vb][0] * inv * silu_f(bflo(gt2.x)), acco[u][vb][1] * inv * silu_f(bfhi(gt2.x)));
;             o.y = cvt_pk_bf16(acco[u][vb][2] * inv * silu_f(bflo(gt2.y)), acco[u][vb][3] * inv * silu_f(bfhi(gt2.y)));
;             *(u32x2*)(y + v0) = o; }
.LBB0_140:
	v_lshl_add_u64 v[64:65], s[50:51], 0, v[152:153]
	v_or_b32_e32 v64, v64, v154
	v_lshl_add_u64 v[66:67], v[64:65], 0, s[12:13]
	v_lshlrev_b64 v[66:67], 8, v[66:67]
	v_lshl_add_u64 v[70:71], v[156:157], 0, v[66:67]
	s_waitcnt vmcnt(0) lgkmcnt(0)
	s_barrier
	v_or_b32_e32 v162, 16, v64
	v_mov_b32_e32 v163, v65
	v_lshl_add_u64 v[162:163], v[162:163], 0, s[12:13]
	v_lshlrev_b64 v[162:163], 8, v[162:163]
	v_lshl_add_u64 v[162:163], v[156:157], 0, v[162:163]
	global_load_dwordx2 v[84:85], v[70:71], off
	global_load_dwordx2 v[86:87], v[70:71], off offset:32
	global_load_dwordx2 v[88:89], v[70:71], off offset:64
	global_load_dwordx2 v[90:91], v[70:71], off offset:96
	global_load_dwordx2 v[92:93], v[70:71], off offset:128
	global_load_dwordx2 v[94:95], v[70:71], off offset:160
	global_load_dwordx2 v[164:165], v[70:71], off offset:192
	global_load_dwordx2 v[166:167], v[70:71], off offset:224
	global_load_dwordx2 v[168:169], v[162:163], off
	global_load_dwordx2 v[170:171], v[162:163], off offset:32
	global_load_dwordx2 v[172:173], v[162:163], off offset:64
	global_load_dwordx2 v[174:175], v[162:163], off offset:96
	global_load_dwordx2 v[228:229], v[162:163], off offset:128
	global_load_dwordx2 v[230:231], v[162:163], off offset:160
	global_load_dwordx2 v[226:227], v[162:163], off offset:192
	global_load_dwordx2 v[162:163], v[162:163], off offset:224
	v_and_b32_e32 v67, 64, v184
	v_xor_b32_e32 v66, 16, v184
	v_add_u32_e32 v67, 64, v67
	v_cmp_lt_i32_e32 vcc, v66, v67
	v_xor_b32_e32 v68, 32, v184
	s_lshl_b32 s0, s10, 7
	v_cndmask_b32_e32 v66, v184, v66, vcc
	v_lshlrev_b32_e32 v69, 2, v66
	ds_bpermute_b32 v73, v69, v225
	v_cmp_lt_i32_e32 vcc, v68, v67
	s_ashr_i32 s1, s0, 31
	v_lshlrev_b64 v[66:67], 12, v[64:65]
	v_cndmask_b32_e32 v68, v184, v68, vcc
	v_lshlrev_b32_e32 v72, 2, v68
	s_waitcnt lgkmcnt(0)
	v_add_f32_e32 v68, v225, v73
	ds_bpermute_b32 v73, v72, v68
	s_lshl_b64 s[0:1], s[0:1], 1
	v_lshl_add_u64 v[66:67], s[18:19], 0, v[66:67]
	v_lshl_add_u64 v[66:67], v[66:67], 0, s[0:1]
	v_lshl_add_u64 v[66:67], v[66:67], 0, v[136:137]
	s_waitcnt lgkmcnt(0)
	v_add_f32_e32 v68, v68, v73
	v_rcp_f32_e32 v68, v68
	v_or_b32_e32 v64, 16, v64
	v_pk_mul_f32 v[60:61], v[60:61], v[68:69] op_sel_hi:[1,0]
	v_pk_mul_f32 v[62:63], v[62:63], v[68:69] op_sel_hi:[1,0]
	v_pk_mul_f32 v[56:57], v[56:57], v[68:69] op_sel_hi:[1,0]
	v_pk_mul_f32 v[58:59], v[58:59], v[68:69] op_sel_hi:[1,0]
	v_pk_mul_f32 v[52:53], v[52:53], v[68:69] op_sel_hi:[1,0]
	v_pk_mul_f32 v[54:55], v[54:55], v[68:69] op_sel_hi:[1,0]
	v_pk_mul_f32 v[48:49], v[48:49], v[68:69] op_sel_hi:[1,0]
	v_pk_mul_f32 v[50:51], v[50:51], v[68:69] op_sel_hi:[1,0]
	v_pk_mul_f32 v[44:45], v[44:45], v[68:69] op_sel_hi:[1,0]
	v_pk_mul_f32 v[46:47], v[46:47], v[68:69] op_sel_hi:[1,0]
	v_pk_mul_f32 v[40:41], v[40:41], v[68:69] op_sel_hi:[1,0]
	v_pk_mul_f32 v[42:43], v[42:43], v[68:69] op_sel_hi:[1,0]
	v_pk_mul_f32 v[36:37], v[36:37], v[68:69] op_sel_hi:[1,0]
	v_pk_mul_f32 v[38:39], v[38:39], v[68:69] op_sel_hi:[1,0]
	v_pk_mul_f32 v[32:33], v[32:33], v[68:69] op_sel_hi:[1,0]
	v_pk_mul_f32 v[34:35], v[34:35], v[68:69] op_sel_hi:[1,0]
	s_waitcnt vmcnt(15)
	v_lshlrev_b32_e32 v76, 16, v84
	v_and_b32_e32 v77, 0xffff0000, v84
	v_lshlrev_b32_e32 v74, 16, v85
	v_and_b32_e32 v75, 0xffff0000, v85
	v_mul_f32_e32 v73, 0xbfb8aa3b, v76
	v_mul_f32_e32 v78, 0xbfb8aa3b, v77
	v_mul_f32_e32 v79, 0xbfb8aa3b, v74
	v_mul_f32_e32 v80, 0xbfb8aa3b, v75
	v_exp_f32_e32 v73, v73
	v_exp_f32_e32 v78, v78
	v_exp_f32_e32 v79, v79
	v_exp_f32_e32 v80, v80
	v_add_f32_e32 v73, 1.0, v73
	v_add_f32_e32 v81, 1.0, v78
	v_add_f32_e32 v82, 1.0, v79
	v_add_f32_e32 v83, 1.0, v80
	v_rcp_f32_e32 v78, v73
	v_rcp_f32_e32 v79, v81
	v_rcp_f32_e32 v80, v82
	v_rcp_f32_e32 v81, v83
	v_pk_mul_f32 v[76:77], v[78:79], v[76:77]
	s_nop 0
	v_pk_mul_f32 v[60:61], v[60:61], v[76:77]
	v_pk_mul_f32 v[74:75], v[80:81], v[74:75]
	v_cvt_pk_bf16_f32 v60, v60, v61
	v_pk_mul_f32 v[62:63], v[62:63], v[74:75]
	s_nop 0
	v_cvt_pk_bf16_f32 v61, v62, v63
	global_store_dwordx2 v[66:67], v[60:61], off offset:1536
	s_waitcnt vmcnt(15)
	v_lshlrev_b32_e32 v62, 16, v86
	v_and_b32_e32 v63, 0xffff0000, v86
	v_lshlrev_b32_e32 v60, 16, v87
	v_and_b32_e32 v61, 0xffff0000, v87
	v_mul_f32_e32 v73, 0xbfb8aa3b, v62
	v_mul_f32_e32 v74, 0xbfb8aa3b, v63
	v_mul_f32_e32 v75, 0xbfb8aa3b, v60
	v_mul_f32_e32 v76, 0xbfb8aa3b, v61
	v_exp_f32_e32 v73, v73
	v_exp_f32_e32 v74, v74
	v_exp_f32_e32 v75, v75
	v_exp_f32_e32 v76, v76
	v_add_f32_e32 v73, 1.0, v73
	v_add_f32_e32 v77, 1.0, v74
	v_add_f32_e32 v78, 1.0, v75
	v_add_f32_e32 v79, 1.0, v76
	v_rcp_f32_e32 v74, v73
	v_rcp_f32_e32 v75, v77
	v_rcp_f32_e32 v76, v78
	v_rcp_f32_e32 v77, v79
	v_pk_mul_f32 v[62:63], v[74:75], v[62:63]
	s_nop 0
	v_pk_mul_f32 v[56:57], v[56:57], v[62:63]
	v_pk_mul_f32 v[60:61], v[76:77], v[60:61]
	v_cvt_pk_bf16_f32 v56, v56, v57
	v_pk_mul_f32 v[58:59], v[58:59], v[60:61]
	s_nop 0
	v_cvt_pk_bf16_f32 v57, v58, v59
	global_store_dwordx2 v[66:67], v[56:57], off offset:1568
	s_waitcnt vmcnt(15)
	v_lshlrev_b32_e32 v58, 16, v88
	v_and_b32_e32 v59, 0xffff0000, v88
	v_lshlrev_b32_e32 v56, 16, v89
	v_and_b32_e32 v57, 0xffff0000, v89
	v_mul_f32_e32 v60, 0xbfb8aa3b, v58
	v_mul_f32_e32 v61, 0xbfb8aa3b, v59
	v_mul_f32_e32 v62, 0xbfb8aa3b, v56
	v_mul_f32_e32 v63, 0xbfb8aa3b, v57
	v_exp_f32_e32 v60, v60
	v_exp_f32_e32 v61, v61
	v_exp_f32_e32 v62, v62
	v_exp_f32_e32 v63, v63
	v_add_f32_e32 v60, 1.0, v60
	v_add_f32_e32 v61, 1.0, v61
	v_add_f32_e32 v62, 1.0, v62
	v_add_f32_e32 v63, 1.0, v63
	v_rcp_f32_e32 v60, v60
	v_rcp_f32_e32 v61, v61
	v_rcp_f32_e32 v62, v62
	v_rcp_f32_e32 v63, v63
	v_pk_mul_f32 v[58:59], v[60:61], v[58:59]
	s_nop 0
	v_pk_mul_f32 v[52:53], v[52:53], v[58:59]
	v_pk_mul_f32 v[56:57], v[62:63], v[56:57]
	v_cvt_pk_bf16_f32 v52, v52, v53
	v_pk_mul_f32 v[54:55], v[54:55], v[56:57]
	s_nop 0
	v_cvt_pk_bf16_f32 v53, v54, v55
	global_store_dwordx2 v[66:67], v[52:53], off offset:1600
	s_waitcnt vmcnt(15)
; __device__ __forceinline__ unsigned cvt_pk_bf16(float lo, float hi) { const f32x2 f = {lo, hi}; const bf16x2_t v = __builtin_convertvector(f, bf16x2_t); return __builtin_bit_cast(unsigned, v); }
; __device__ __forceinline__ float bflo(unsigned u) { return __uint_as_float(u << 16); }
; __device__ __forceinline__ float bfhi(unsigned u) { return __uint_as_float(u & 0xffff0000u); }
; __device__ __forceinline__ float rcp_f(float v) { return __builtin_amdgcn_rcpf(v); }
; __device__ __forceinline__ float silu_f(float v) { return v * rcp_f(1.f + __expf(-v)); }
; __device__ __forceinline__ void b_item(const Params& P, int layer, LAS unsigned char* lds, int item, int tid) {
;     ...
;     for (int u = 0; u < 2; ++u) {
;         float l = lrun[u]; l += __shfl_xor(l, 16); l += __shfl_xor(l, 32);
;         const float inv = rcp_f(l);
;         const size_t tok = tok0 + 64 * qc + 32 * th + 16 * u + c15;
;         const bf16_t* gate = pjp(proj, BG, 128, h, tok);
;         bf16_t* y = (bf16_t*)(P.ws + (layer == 0 ? WS_H : WS_D1)) + tok * DM + YB + h * 128;
; #pragma unroll
;         for (int vb = 0; vb < 8; ++vb) { const int v0 = 16 * vb + 4 * g; const u32x2 gt2 = *(const u32x2*)(gate + v0);
;             u32x2 o; o.x = cvt_pk_bf16(acco[u][vb][0] * inv * silu_f(bflo(gt2.x)), acco[u][vb][1] * inv * silu_f(bfhi(gt2.x)));
;             o.y = cvt_pk_bf16(acco[u][vb][2] * inv * silu_f(bflo(gt2.y)), acco[u][vb][3] * inv * silu_f(bfhi(gt2.y)));
;             *(u32x2*)(y + v0) = o; }
	v_lshlrev_b32_e32 v54, 16, v90
	v_and_b32_e32 v55, 0xffff0000, v90
	v_lshlrev_b32_e32 v52, 16, v91
	v_and_b32_e32 v53, 0xffff0000, v91
	v_mul_f32_e32 v56, 0xbfb8aa3b, v54
	v_mul_f32_e32 v57, 0xbfb8aa3b, v55
	v_mul_f32_e32 v58, 0xbfb8aa3b, v52
	v_mul_f32_e32 v59, 0xbfb8aa3b, v53
	v_exp_f32_e32 v56, v56
	v_exp_f32_e32 v57, v57
	v_exp_f32_e32 v58, v58
	v_exp_f32_e32 v59, v59
	v_add_f32_e32 v56, 1.0, v56
	v_add_f32_e32 v57, 1.0, v57
	v_add_f32_e32 v58, 1.0, v58
	v_add_f32_e32 v59, 1.0, v59
	v_rcp_f32_e32 v56, v56
	v_rcp_f32_e32 v57, v57
	v_rcp_f32_e32 v58, v58
	v_rcp_f32_e32 v59, v59
	v_pk_mul_f32 v[54:55], v[56:57], v[54:55]
	s_nop 0
	v_pk_mul_f32 v[48:49], v[48:49], v[54:55]
	v_pk_mul_f32 v[52:53], v[58:59], v[52:53]
	v_cvt_pk_bf16_f32 v48, v48, v49
	v_pk_mul_f32 v[50:51], v[50:51], v[52:53]
	s_nop 0
	v_cvt_pk_bf16_f32 v49, v50, v51
	global_store_dwordx2 v[66:67], v[48:49], off offset:1632
	s_waitcnt vmcnt(15)
	v_lshlrev_b32_e32 v50, 16, v92
	v_and_b32_e32 v51, 0xffff0000, v92
	v_lshlrev_b32_e32 v48, 16, v93
	v_and_b32_e32 v49, 0xffff0000, v93
	v_mul_f32_e32 v52, 0xbfb8aa3b, v50
	v_mul_f32_e32 v53, 0xbfb8aa3b, v51
	v_mul_f32_e32 v54, 0xbfb8aa3b, v48
	v_mul_f32_e32 v55, 0xbfb8aa3b, v49
	v_exp_f32_e32 v52, v52
	v_exp_f32_e32 v53, v53
	v_exp_f32_e32 v54, v54
	v_exp_f32_e32 v55, v55
	v_add_f32_e32 v52, 1.0, v52
	v_add_f32_e32 v53, 1.0, v53
	v_add_f32_e32 v54, 1.0, v54
	v_add_f32_e32 v55, 1.0, v55
	v_rcp_f32_e32 v52, v52
	v_rcp_f32_e32 v53, v53
	v_rcp_f32_e32 v54, v54
	v_rcp_f32_e32 v55, v55
	v_pk_mul_f32 v[50:51], v[52:53], v[50:51]
	s_nop 0
	v_pk_mul_f32 v[44:45], v[44:45], v[50:51]
	v_pk_mul_f32 v[48:49], v[54:55], v[48:49]
	v_cvt_pk_bf16_f32 v44, v44, v45
	v_pk_mul_f32 v[46:47], v[46:47], v[48:49]
	s_nop 0
	v_cvt_pk_bf16_f32 v45, v46, v47
	global_store_dwordx2 v[66:67], v[44:45], off offset:1664
	s_waitcnt vmcnt(15)
	v_lshlrev_b32_e32 v46, 16, v94
	v_and_b32_e32 v47, 0xffff0000, v94
	v_lshlrev_b32_e32 v44, 16, v95
	v_and_b32_e32 v45, 0xffff0000, v95
	v_mul_f32_e32 v48, 0xbfb8aa3b, v46
	v_mul_f32_e32 v49, 0xbfb8aa3b, v47
	v_mul_f32_e32 v50, 0xbfb8aa3b, v44
	v_mul_f32_e32 v51, 0xbfb8aa3b, v45
	v_exp_f32_e32 v48, v48
	v_exp_f32_e32 v49, v49
	v_exp_f32_e32 v50, v50
	v_exp_f32_e32 v51, v51
	v_add_f32_e32 v48, 1.0, v48
	v_add_f32_e32 v49, 1.0, v49
	v_add_f32_e32 v50, 1.0, v50
	v_add_f32_e32 v51, 1.0, v51
	v_rcp_f32_e32 v48, v48
	v_rcp_f32_e32 v49, v49
	v_rcp_f32_e32 v50, v50
	v_rcp_f32_e32 v51, v51
	v_pk_mul_f32 v[46:47], v[48:49], v[46:47]
	s_nop 0
	v_pk_mul_f32 v[40:41], v[40:41], v[46:47]
	v_pk_mul_f32 v[44:45], v[50:51], v[44:45]
	v_cvt_pk_bf16_f32 v40, v40, v41
	v_pk_mul_f32 v[42:43], v[42:43], v[44:45]
	s_nop 0
	v_cvt_pk_bf16_f32 v41, v42, v43
	global_store_dwordx2 v[66:67], v[40:41], off offset:1696
	s_waitcnt vmcnt(15)
	v_lshlrev_b32_e32 v42, 16, v164
	v_and_b32_e32 v43, 0xffff0000, v164
	v_lshlrev_b32_e32 v40, 16, v165
	v_and_b32_e32 v41, 0xffff0000, v165
	v_mul_f32_e32 v44, 0xbfb8aa3b, v42
	v_mul_f32_e32 v45, 0xbfb8aa3b, v43
	v_mul_f32_e32 v46, 0xbfb8aa3b, v40
	v_mul_f32_e32 v47, 0xbfb8aa3b, v41
	v_exp_f32_e32 v44, v44
	v_exp_f32_e32 v45, v45
	v_exp_f32_e32 v46, v46
	v_exp_f32_e32 v47, v47
	v_add_f32_e32 v44, 1.0, v44
	v_add_f32_e32 v45, 1.0, v45
	v_add_f32_e32 v46, 1.0, v46
	v_add_f32_e32 v47, 1.0, v47
	v_rcp_f32_e32 v44, v44
	v_rcp_f32_e32 v45, v45
	v_rcp_f32_e32 v46, v46
	v_rcp_f32_e32 v47, v47
	v_pk_mul_f32 v[42:43], v[44:45], v[42:43]
	s_nop 0
	v_pk_mul_f32 v[36:37], v[36:37], v[42:43]
	v_pk_mul_f32 v[40:41], v[46:47], v[40:41]
	v_cvt_pk_bf16_f32 v36, v36, v37
	v_pk_mul_f32 v[38:39], v[38:39], v[40:41]
	s_nop 0
	v_cvt_pk_bf16_f32 v37, v38, v39
	global_store_dwordx2 v[66:67], v[36:37], off offset:1728
	v_lshl_add_u64 v[36:37], v[64:65], 0, s[12:13]
	v_lshlrev_b64 v[36:37], 8, v[36:37]
	v_lshl_add_u64 v[36:37], v[156:157], 0, v[36:37]
	s_waitcnt vmcnt(15)
	v_lshlrev_b32_e32 v40, 16, v166
	v_and_b32_e32 v41, 0xffff0000, v166
	v_lshlrev_b32_e32 v38, 16, v167
	v_and_b32_e32 v39, 0xffff0000, v167
	v_mul_f32_e32 v42, 0xbfb8aa3b, v40
	v_mul_f32_e32 v43, 0xbfb8aa3b, v41
	v_mul_f32_e32 v44, 0xbfb8aa3b, v38
	v_mul_f32_e32 v45, 0xbfb8aa3b, v39
	v_exp_f32_e32 v42, v42
	v_exp_f32_e32 v43, v43
	v_exp_f32_e32 v44, v44
	v_exp_f32_e32 v45, v45
	v_add_f32_e32 v42, 1.0, v42
	v_add_f32_e32 v43, 1.0, v43
	v_add_f32_e32 v44, 1.0, v44
	v_add_f32_e32 v45, 1.0, v45
	v_rcp_f32_e32 v42, v42
	v_rcp_f32_e32 v43, v43
	v_rcp_f32_e32 v44, v44
	v_rcp_f32_e32 v45, v45
	v_pk_mul_f32 v[40:41], v[42:43], v[40:41]
	s_nop 0
	v_pk_mul_f32 v[32:33], v[32:33], v[40:41]
	v_pk_mul_f32 v[38:39], v[44:45], v[38:39]
	v_cvt_pk_bf16_f32 v32, v32, v33
	v_pk_mul_f32 v[34:35], v[34:35], v[38:39]
	s_nop 0
	v_cvt_pk_bf16_f32 v33, v34, v35
	global_store_dwordx2 v[66:67], v[32:33], off offset:1760
	ds_bpermute_b32 v32, v69, v224
	s_waitcnt lgkmcnt(0)
	v_add_f32_e32 v34, v224, v32
	ds_bpermute_b32 v35, v72, v34
	v_lshlrev_b64 v[32:33], 12, v[64:65]
	v_lshl_add_u64 v[32:33], s[18:19], 0, v[32:33]
	v_lshl_add_u64 v[32:33], v[32:33], 0, s[0:1]
	v_lshl_add_u64 v[32:33], v[32:33], 0, v[136:137]
	s_waitcnt lgkmcnt(0)
	v_add_f32_e32 v34, v34, v35
	v_rcp_f32_e32 v34, v34
	s_mov_b64 s[0:1], 0
	s_waitcnt vmcnt(15)
; __device__ __forceinline__ unsigned cvt_pk_bf16(float lo, float hi) { const f32x2 f = {lo, hi}; const bf16x2_t v = __builtin_convertvector(f, bf16x2_t); return __builtin_bit_cast(unsigned, v); }
; __device__ __forceinline__ float bflo(unsigned u) { return __uint_as_float(u << 16); }
; __device__ __forceinline__ float bfhi(unsigned u) { return __uint_as_float(u & 0xffff0000u); }
; __device__ __forceinline__ float rcp_f(float v) { return __builtin_amdgcn_rcpf(v); }
; __device__ __forceinline__ float silu_f(float v) { return v * rcp_f(1.f + __expf(-v)); }
; __device__ __forceinline__ void b_item(const Params& P, int layer, LAS unsigned char* lds, int item, int tid) {
;     ...
;     for (int u = 0; u < 2; ++u) {
;         float l = lrun[u]; l += __shfl_xor(l, 16); l += __shfl_xor(l, 32);
;         const float inv = rcp_f(l);
;         const size_t tok = tok0 + 64 * qc + 32 * th + 16 * u + c15;
;         const bf16_t* gate = pjp(proj, BG, 128, h, tok);
;         bf16_t* y = (bf16_t*)(P.ws + (layer == 0 ? WS_H : WS_D1)) + tok * DM + YB + h * 128;
; #pragma unroll
;         for (int vb = 0; vb < 8; ++vb) { const int v0 = 16 * vb + 4 * g; const u32x2 gt2 = *(const u32x2*)(gate + v0);
;             u32x2 o; o.x = cvt_pk_bf16(acco[u][vb][0] * inv * silu_f(bflo(gt2.x)), acco[u][vb][1] * inv * silu_f(bfhi(gt2.x)));
;             o.y = cvt_pk_bf16(acco[u][vb][2] * inv * silu_f(bflo(gt2.y)), acco[u][vb][3] * inv * silu_f(bfhi(gt2.y)));
;             *(u32x2*)(y + v0) = o; }
	v_lshlrev_b32_e32 v40, 16, v168
	v_and_b32_e32 v41, 0xffff0000, v168
	v_lshlrev_b32_e32 v38, 16, v169
	v_and_b32_e32 v39, 0xffff0000, v169
	v_mul_f32_e32 v35, 0xbfb8aa3b, v40
	v_mul_f32_e32 v42, 0xbfb8aa3b, v41
	v_mul_f32_e32 v43, 0xbfb8aa3b, v38
	v_mul_f32_e32 v44, 0xbfb8aa3b, v39
	v_exp_f32_e32 v35, v35
	v_exp_f32_e32 v42, v42
	v_exp_f32_e32 v43, v43
	v_exp_f32_e32 v44, v44
	v_add_f32_e32 v35, 1.0, v35
	v_add_f32_e32 v45, 1.0, v42
	v_add_f32_e32 v46, 1.0, v43
	v_add_f32_e32 v47, 1.0, v44
	v_rcp_f32_e32 v42, v35
	v_rcp_f32_e32 v43, v45
	v_rcp_f32_e32 v44, v46
	v_rcp_f32_e32 v45, v47
	v_pk_mul_f32 v[28:29], v[28:29], v[34:35] op_sel_hi:[1,0]
	v_pk_mul_f32 v[30:31], v[30:31], v[34:35] op_sel_hi:[1,0]
	v_pk_mul_f32 v[40:41], v[42:43], v[40:41]
	v_pk_mul_f32 v[38:39], v[44:45], v[38:39]
	v_pk_mul_f32 v[28:29], v[28:29], v[40:41]
	v_pk_mul_f32 v[30:31], v[30:31], v[38:39]
	v_cvt_pk_bf16_f32 v28, v28, v29
	v_cvt_pk_bf16_f32 v29, v30, v31
	global_store_dwordx2 v[32:33], v[28:29], off offset:1536
	s_waitcnt vmcnt(15)
	v_lshlrev_b32_e32 v30, 16, v170
	v_and_b32_e32 v31, 0xffff0000, v170
	v_lshlrev_b32_e32 v28, 16, v171
	v_and_b32_e32 v29, 0xffff0000, v171
	v_mul_f32_e32 v35, 0xbfb8aa3b, v30
	v_mul_f32_e32 v38, 0xbfb8aa3b, v31
	v_mul_f32_e32 v39, 0xbfb8aa3b, v28
	v_mul_f32_e32 v40, 0xbfb8aa3b, v29
	v_exp_f32_e32 v35, v35
	v_exp_f32_e32 v38, v38
	v_exp_f32_e32 v39, v39
	v_exp_f32_e32 v40, v40
	v_add_f32_e32 v35, 1.0, v35
	v_add_f32_e32 v41, 1.0, v38
	v_add_f32_e32 v42, 1.0, v39
	v_add_f32_e32 v43, 1.0, v40
	v_rcp_f32_e32 v38, v35
	v_rcp_f32_e32 v39, v41
	v_rcp_f32_e32 v40, v42
	v_rcp_f32_e32 v41, v43
	v_pk_mul_f32 v[24:25], v[24:25], v[34:35] op_sel_hi:[1,0]
	v_pk_mul_f32 v[26:27], v[26:27], v[34:35] op_sel_hi:[1,0]
	v_pk_mul_f32 v[30:31], v[38:39], v[30:31]
	v_pk_mul_f32 v[28:29], v[40:41], v[28:29]
	v_pk_mul_f32 v[24:25], v[24:25], v[30:31]
	v_pk_mul_f32 v[26:27], v[26:27], v[28:29]
	v_cvt_pk_bf16_f32 v24, v24, v25
	v_cvt_pk_bf16_f32 v25, v26, v27
	global_store_dwordx2 v[32:33], v[24:25], off offset:1568
	v_pk_mul_f32 v[20:21], v[20:21], v[34:35] op_sel_hi:[1,0]
	v_pk_mul_f32 v[22:23], v[22:23], v[34:35] op_sel_hi:[1,0]
	v_pk_mul_f32 v[16:17], v[16:17], v[34:35] op_sel_hi:[1,0]
	v_pk_mul_f32 v[18:19], v[18:19], v[34:35] op_sel_hi:[1,0]
	v_pk_mul_f32 v[12:13], v[12:13], v[34:35] op_sel_hi:[1,0]
	v_pk_mul_f32 v[14:15], v[14:15], v[34:35] op_sel_hi:[1,0]
	v_pk_mul_f32 v[8:9], v[8:9], v[34:35] op_sel_hi:[1,0]
	v_pk_mul_f32 v[10:11], v[10:11], v[34:35] op_sel_hi:[1,0]
	v_pk_mul_f32 v[4:5], v[4:5], v[34:35] op_sel_hi:[1,0]
	v_pk_mul_f32 v[6:7], v[6:7], v[34:35] op_sel_hi:[1,0]
	v_pk_mul_f32 v[0:1], v[0:1], v[34:35] op_sel_hi:[1,0]
	v_pk_mul_f32 v[2:3], v[2:3], v[34:35] op_sel_hi:[1,0]
	s_waitcnt vmcnt(15)
	v_lshlrev_b32_e32 v26, 16, v172
	v_and_b32_e32 v27, 0xffff0000, v172
	v_lshlrev_b32_e32 v24, 16, v173
	v_and_b32_e32 v25, 0xffff0000, v173
	v_mul_f32_e32 v28, 0xbfb8aa3b, v26
	v_mul_f32_e32 v29, 0xbfb8aa3b, v27
	v_mul_f32_e32 v30, 0xbfb8aa3b, v24
	v_mul_f32_e32 v31, 0xbfb8aa3b, v25
	v_exp_f32_e32 v28, v28
	v_exp_f32_e32 v29, v29
	v_exp_f32_e32 v30, v30
	v_exp_f32_e32 v31, v31
	v_add_f32_e32 v28, 1.0, v28
	v_add_f32_e32 v29, 1.0, v29
	v_add_f32_e32 v30, 1.0, v30
	v_add_f32_e32 v31, 1.0, v31
	v_rcp_f32_e32 v28, v28
	v_rcp_f32_e32 v29, v29
	v_rcp_f32_e32 v30, v30
	v_rcp_f32_e32 v31, v31
	v_pk_mul_f32 v[26:27], v[28:29], v[26:27]
	s_nop 0
	v_pk_mul_f32 v[20:21], v[20:21], v[26:27]
	v_pk_mul_f32 v[24:25], v[30:31], v[24:25]
	v_cvt_pk_bf16_f32 v20, v20, v21
	v_pk_mul_f32 v[22:23], v[22:23], v[24:25]
	s_nop 0
	v_cvt_pk_bf16_f32 v21, v22, v23
	global_store_dwordx2 v[32:33], v[20:21], off offset:1600
	s_waitcnt vmcnt(15)
; __device__ __forceinline__ unsigned cvt_pk_bf16(float lo, float hi) { const f32x2 f = {lo, hi}; const bf16x2_t v = __builtin_convertvector(f, bf16x2_t); return __builtin_bit_cast(unsigned, v); }
; __device__ __forceinline__ float bflo(unsigned u) { return __uint_as_float(u << 16); }
; __device__ __forceinline__ float bfhi(unsigned u) { return __uint_as_float(u & 0xffff0000u); }
; __device__ __forceinline__ float silu_f(float v) { return v * rcp_f(1.f + __expf(-v)); }
; __device__ __forceinline__ void b_item(const Params& P, int layer, LAS unsigned char* lds, int item, int tid) {
;     ...
;         for (int vb = 0; vb < 8; ++vb) { const int v0 = 16 * vb + 4 * g; const u32x2 gt2 = *(const u32x2*)(gate + v0);
;             u32x2 o; o.x = cvt_pk_bf16(acco[u][vb][0] * inv * silu_f(bflo(gt2.x)), acco[u][vb][1] * inv * silu_f(bfhi(gt2.x)));
;             o.y = cvt_pk_bf16(acco[u][vb][2] * inv * silu_f(bflo(gt2.y)), acco[u][vb][3] * inv * silu_f(bfhi(gt2.y)));
;             *(u32x2*)(y + v0) = o; }
	v_lshlrev_b32_e32 v22, 16, v174
	v_and_b32_e32 v23, 0xffff0000, v174
	v_lshlrev_b32_e32 v20, 16, v175
	v_and_b32_e32 v21, 0xffff0000, v175
	v_mul_f32_e32 v24, 0xbfb8aa3b, v22
	v_mul_f32_e32 v25, 0xbfb8aa3b, v23
	v_mul_f32_e32 v26, 0xbfb8aa3b, v20
	v_mul_f32_e32 v27, 0xbfb8aa3b, v21
	v_exp_f32_e32 v24, v24
	v_exp_f32_e32 v25, v25
	v_exp_f32_e32 v26, v26
	v_exp_f32_e32 v27, v27
	v_add_f32_e32 v24, 1.0, v24
	v_add_f32_e32 v25, 1.0, v25
	v_add_f32_e32 v26, 1.0, v26
	v_add_f32_e32 v27, 1.0, v27
	v_rcp_f32_e32 v24, v24
	v_rcp_f32_e32 v25, v25
	v_rcp_f32_e32 v26, v26
	v_rcp_f32_e32 v27, v27
	v_pk_mul_f32 v[22:23], v[24:25], v[22:23]
	s_nop 0
	v_pk_mul_f32 v[16:17], v[16:17], v[22:23]
	v_pk_mul_f32 v[20:21], v[26:27], v[20:21]
	v_cvt_pk_bf16_f32 v16, v16, v17
	v_pk_mul_f32 v[18:19], v[18:19], v[20:21]
	s_nop 0
	v_cvt_pk_bf16_f32 v17, v18, v19
	global_store_dwordx2 v[32:33], v[16:17], off offset:1632
	s_waitcnt vmcnt(15)
	v_lshlrev_b32_e32 v18, 16, v228
	v_and_b32_e32 v19, 0xffff0000, v228
	v_lshlrev_b32_e32 v16, 16, v229
	v_and_b32_e32 v17, 0xffff0000, v229
	v_mul_f32_e32 v20, 0xbfb8aa3b, v18
	v_mul_f32_e32 v21, 0xbfb8aa3b, v19
	v_mul_f32_e32 v22, 0xbfb8aa3b, v16
	v_mul_f32_e32 v23, 0xbfb8aa3b, v17
	v_exp_f32_e32 v20, v20
	v_exp_f32_e32 v21, v21
	v_exp_f32_e32 v22, v22
	v_exp_f32_e32 v23, v23
	v_add_f32_e32 v20, 1.0, v20
	v_add_f32_e32 v21, 1.0, v21
	v_add_f32_e32 v22, 1.0, v22
	v_add_f32_e32 v23, 1.0, v23
	v_rcp_f32_e32 v20, v20
	v_rcp_f32_e32 v21, v21
	v_rcp_f32_e32 v22, v22
	v_rcp_f32_e32 v23, v23
	v_pk_mul_f32 v[18:19], v[20:21], v[18:19]
	s_nop 0
	v_pk_mul_f32 v[12:13], v[12:13], v[18:19]
	v_pk_mul_f32 v[16:17], v[22:23], v[16:17]
	v_cvt_pk_bf16_f32 v12, v12, v13
	v_pk_mul_f32 v[14:15], v[14:15], v[16:17]
	s_nop 0
	v_cvt_pk_bf16_f32 v13, v14, v15
	global_store_dwordx2 v[32:33], v[12:13], off offset:1664
	s_waitcnt vmcnt(15)
	v_lshlrev_b32_e32 v14, 16, v230
	v_and_b32_e32 v15, 0xffff0000, v230
	v_lshlrev_b32_e32 v12, 16, v231
	v_and_b32_e32 v13, 0xffff0000, v231
	v_mul_f32_e32 v16, 0xbfb8aa3b, v14
	v_mul_f32_e32 v17, 0xbfb8aa3b, v15
	v_mul_f32_e32 v18, 0xbfb8aa3b, v12
	v_mul_f32_e32 v19, 0xbfb8aa3b, v13
	v_exp_f32_e32 v16, v16
	v_exp_f32_e32 v17, v17
	v_exp_f32_e32 v18, v18
	v_exp_f32_e32 v19, v19
	v_add_f32_e32 v16, 1.0, v16
	v_add_f32_e32 v17, 1.0, v17
	v_add_f32_e32 v18, 1.0, v18
	v_add_f32_e32 v19, 1.0, v19
	v_rcp_f32_e32 v16, v16
	v_rcp_f32_e32 v17, v17
	v_rcp_f32_e32 v18, v18
	v_rcp_f32_e32 v19, v19
	v_pk_mul_f32 v[14:15], v[16:17], v[14:15]
	s_nop 0
	v_pk_mul_f32 v[8:9], v[8:9], v[14:15]
	v_pk_mul_f32 v[12:13], v[18:19], v[12:13]
	v_cvt_pk_bf16_f32 v8, v8, v9
	v_pk_mul_f32 v[10:11], v[10:11], v[12:13]
	s_nop 0
	v_cvt_pk_bf16_f32 v9, v10, v11
	global_store_dwordx2 v[32:33], v[8:9], off offset:1696
	s_waitcnt vmcnt(15)
	v_lshlrev_b32_e32 v10, 16, v226
	v_and_b32_e32 v11, 0xffff0000, v226
	v_lshlrev_b32_e32 v8, 16, v227
	v_and_b32_e32 v9, 0xffff0000, v227
	v_mul_f32_e32 v12, 0xbfb8aa3b, v10
	v_mul_f32_e32 v13, 0xbfb8aa3b, v11
	v_mul_f32_e32 v14, 0xbfb8aa3b, v8
	v_mul_f32_e32 v15, 0xbfb8aa3b, v9
	v_exp_f32_e32 v12, v12
	v_exp_f32_e32 v13, v13
	v_exp_f32_e32 v14, v14
	v_exp_f32_e32 v15, v15
	v_add_f32_e32 v12, 1.0, v12
	v_add_f32_e32 v13, 1.0, v13
	v_add_f32_e32 v14, 1.0, v14
	v_add_f32_e32 v15, 1.0, v15
	v_rcp_f32_e32 v12, v12
	v_rcp_f32_e32 v13, v13
	v_rcp_f32_e32 v14, v14
	v_rcp_f32_e32 v15, v15
	v_pk_mul_f32 v[10:11], v[12:13], v[10:11]
	s_nop 0
	v_pk_mul_f32 v[4:5], v[4:5], v[10:11]
	v_pk_mul_f32 v[8:9], v[14:15], v[8:9]
	v_cvt_pk_bf16_f32 v4, v4, v5
	v_pk_mul_f32 v[6:7], v[6:7], v[8:9]
	s_nop 0
	v_cvt_pk_bf16_f32 v5, v6, v7
	global_store_dwordx2 v[32:33], v[4:5], off offset:1728
	s_waitcnt vmcnt(15)
	v_lshlrev_b32_e32 v6, 16, v162
	v_and_b32_e32 v7, 0xffff0000, v162
	v_lshlrev_b32_e32 v4, 16, v163
	v_and_b32_e32 v5, 0xffff0000, v163
	v_mul_f32_e32 v8, 0xbfb8aa3b, v6
	v_mul_f32_e32 v9, 0xbfb8aa3b, v7
	v_mul_f32_e32 v10, 0xbfb8aa3b, v4
	v_mul_f32_e32 v11, 0xbfb8aa3b, v5
	v_exp_f32_e32 v8, v8
	v_exp_f32_e32 v9, v9
	v_exp_f32_e32 v10, v10
	v_exp_f32_e32 v11, v11
	v_add_f32_e32 v8, 1.0, v8
	v_add_f32_e32 v9, 1.0, v9
	v_add_f32_e32 v10, 1.0, v10
	v_add_f32_e32 v11, 1.0, v11
	v_rcp_f32_e32 v8, v8
	v_rcp_f32_e32 v9, v9
	v_rcp_f32_e32 v10, v10
	v_rcp_f32_e32 v11, v11
	v_pk_mul_f32 v[6:7], v[8:9], v[6:7]
	s_nop 0
	v_pk_mul_f32 v[0:1], v[0:1], v[6:7]
	v_pk_mul_f32 v[4:5], v[10:11], v[4:5]
	v_cvt_pk_bf16_f32 v0, v0, v1
	v_pk_mul_f32 v[2:3], v[2:3], v[4:5]
	s_nop 0
	v_cvt_pk_bf16_f32 v1, v2, v3
	global_store_dwordx2 v[32:33], v[0:1], off offset:1760

; __device__ __forceinline__ float bflo(unsigned u) { return __uint_as_float(u << 16); }
; __device__ __forceinline__ float bfhi(unsigned u) { return __uint_as_float(u & 0xffff0000u); }
; __device__ __forceinline__ void phase_final(const bf16_t* h1, const bf16_t* d2, const float* rr, const float* g1, const float* gain, float* dst, int tid) {
;     ...
;     for (int row = blockIdx.x * 8 + wave; row < NTOK; row += gridDim.x * 8) {
;         const float sc = rr[row];
;         f32x4 v[8]; float ss = 0.f;
; #pragma unroll
;         for (int j = 0; j < 8; ++j) { const u32x2 p = *(const u32x2*)(h1 + (size_t)row * DM + 4 * (lane + 64 * j)), q = *(const u32x2*)(d2 + (size_t)row * DM + 4 * (lane + 64 * j));
;             v[j][0] = bflo(p.x) * sc * ig[j][0] + bflo(q.x); v[j][1] = bfhi(p.x) * sc * ig[j][1] + bfhi(q.x); v[j][2] = bflo(p.y) * sc * ig[j][2] + bflo(q.y); v[j][3] = bfhi(p.y) * sc * ig[j][3] + bfhi(q.y);
;             ss += (v[j][0] * v[j][0] + v[j][1] * v[j][1]) + (v[j][2] * v[j][2] + v[j][3] * v[j][3]); }
;         const float r = rsqrtf(wave_sum(ss) * (1.f / DM) + EPSN);
.LBB0_228:
	v_ashrrev_i32_e32 v33, 31, v32
	v_lshl_add_u64 v[78:79], v[32:33], 2, s[12:13]
	global_load_dword v82, v[78:79], off
	v_lshlrev_b64 v[78:79], 12, v[32:33]
	v_lshl_add_u64 v[106:107], v[66:67], 0, v[78:79]
	global_load_dwordx2 v[80:81], v[106:107], off
	v_lshl_add_u64 v[108:109], v[68:69], 0, v[78:79]
	global_load_dwordx2 v[84:85], v[108:109], off
	global_load_dwordx2 v[156:157], v[106:107], off offset:512
	global_load_dwordx2 v[158:159], v[108:109], off offset:512
	global_load_dwordx2 v[160:161], v[106:107], off offset:1024
	global_load_dwordx2 v[162:163], v[108:109], off offset:1024
	global_load_dwordx2 v[164:165], v[106:107], off offset:1536
	global_load_dwordx2 v[166:167], v[108:109], off offset:1536
	global_load_dwordx2 v[168:169], v[106:107], off offset:2048
	global_load_dwordx2 v[170:171], v[108:109], off offset:2048
	global_load_dwordx2 v[172:173], v[106:107], off offset:2560
	global_load_dwordx2 v[174:175], v[108:109], off offset:2560
	global_load_dwordx2 v[190:191], v[106:107], off offset:3072
	global_load_dwordx2 v[192:193], v[108:109], off offset:3072
	global_load_dwordx2 v[194:195], v[106:107], off offset:3584
	global_load_dwordx2 v[196:197], v[108:109], off offset:3584
	v_mov_b32_e32 v75, v137
	v_mov_b32_e32 v77, v137
	s_waitcnt vmcnt(14)
	v_lshlrev_b32_e32 v78, 16, v80
	v_and_b32_e32 v79, 0xffff0000, v80
	v_pk_mul_f32 v[78:79], v[82:83], v[78:79] op_sel_hi:[0,1]
	v_lshlrev_b32_e32 v86, 16, v84
	v_and_b32_e32 v87, 0xffff0000, v84
	v_pk_fma_f32 v[78:79], v[64:65], v[78:79], v[86:87]
	v_lshlrev_b32_e32 v80, 16, v81
	v_and_b32_e32 v81, 0xffff0000, v81
	v_pk_mul_f32 v[80:81], v[82:83], v[80:81] op_sel_hi:[0,1]
	v_lshlrev_b32_e32 v84, 16, v85
	v_and_b32_e32 v85, 0xffff0000, v85
	v_pk_fma_f32 v[80:81], v[62:63], v[80:81], v[84:85]
	s_waitcnt vmcnt(12)
	v_mov_b32_e32 v86, v156
	v_mov_b32_e32 v87, v157
	v_mov_b32_e32 v88, v158
	v_mov_b32_e32 v89, v159
	v_lshlrev_b32_e32 v84, 16, v86
	v_and_b32_e32 v85, 0xffff0000, v86
	v_pk_mul_f32 v[84:85], v[82:83], v[84:85] op_sel_hi:[0,1]
	v_lshlrev_b32_e32 v90, 16, v88
	v_and_b32_e32 v91, 0xffff0000, v88
	v_pk_fma_f32 v[84:85], v[60:61], v[84:85], v[90:91]
	v_lshlrev_b32_e32 v86, 16, v87
	v_and_b32_e32 v87, 0xffff0000, v87
	v_pk_mul_f32 v[86:87], v[82:83], v[86:87] op_sel_hi:[0,1]
	v_lshlrev_b32_e32 v88, 16, v89
	v_and_b32_e32 v89, 0xffff0000, v89
	v_mov_b32_e32 v90, v79
	v_mov_b32_e32 v91, v85
	v_pk_fma_f32 v[86:87], v[58:59], v[86:87], v[88:89]
	v_mov_b32_e32 v88, v78
	v_mov_b32_e32 v89, v84
	v_pk_mul_f32 v[90:91], v[90:91], v[90:91]
	v_mov_b32_e32 v92, v81
	v_pk_fma_f32 v[88:89], v[88:89], v[88:89], v[90:91]
	v_mov_b32_e32 v90, v80
	v_mov_b32_e32 v91, v86
	v_pk_mul_f32 v[90:91], v[90:91], v[90:91]
	v_mov_b32_e32 v93, v87
	v_pk_fma_f32 v[90:91], v[92:93], v[92:93], v[90:91]
	s_nop 0
	v_pk_add_f32 v[88:89], v[88:89], v[90:91]
	v_pk_add_f32 v[100:101], v[88:89], v[88:89] op_sel:[0,1] op_sel_hi:[1,0]
	s_waitcnt vmcnt(10)
	v_mov_b32_e32 v90, v160
	v_mov_b32_e32 v91, v161
	v_mov_b32_e32 v92, v162
	v_mov_b32_e32 v93, v163
	v_lshlrev_b32_e32 v88, 16, v90
	v_and_b32_e32 v89, 0xffff0000, v90
	v_lshlrev_b32_e32 v90, 16, v91
	v_and_b32_e32 v91, 0xffff0000, v91
	v_pk_mul_f32 v[88:89], v[82:83], v[88:89] op_sel_hi:[0,1]
	v_lshlrev_b32_e32 v94, 16, v92
	v_and_b32_e32 v95, 0xffff0000, v92
	v_pk_mul_f32 v[90:91], v[82:83], v[90:91] op_sel_hi:[0,1]
	v_lshlrev_b32_e32 v92, 16, v93
	v_and_b32_e32 v93, 0xffff0000, v93
	v_pk_fma_f32 v[88:89], v[56:57], v[88:89], v[94:95]
	v_pk_fma_f32 v[90:91], v[54:55], v[90:91], v[92:93]
	v_mov_b32_e32 v94, v88
	v_pk_mov_b32 v[92:93], v[88:89], v[90:91] op_sel:[1,0]
	v_mov_b32_e32 v95, v91
	v_pk_mul_f32 v[92:93], v[92:93], v[92:93]
	s_nop 0
	v_pk_fma_f32 v[92:93], v[94:95], v[94:95], v[92:93]
	v_pk_add_f32 v[102:103], v[92:93], v[92:93] op_sel:[0,1] op_sel_hi:[1,0]
	s_waitcnt vmcnt(8)
	v_mov_b32_e32 v94, v164
	v_mov_b32_e32 v95, v165
	v_mov_b32_e32 v96, v166
	v_mov_b32_e32 v97, v167
	v_lshlrev_b32_e32 v92, 16, v94
	v_and_b32_e32 v93, 0xffff0000, v94
	v_pk_mul_f32 v[92:93], v[82:83], v[92:93] op_sel_hi:[0,1]
	v_lshlrev_b32_e32 v98, 16, v96
	v_and_b32_e32 v99, 0xffff0000, v96
	v_pk_fma_f32 v[92:93], v[52:53], v[92:93], v[98:99]
	v_lshlrev_b32_e32 v94, 16, v95
	v_and_b32_e32 v95, 0xffff0000, v95
	v_pk_mul_f32 v[94:95], v[82:83], v[94:95] op_sel_hi:[0,1]
	v_lshlrev_b32_e32 v96, 16, v97
	v_and_b32_e32 v97, 0xffff0000, v97
	v_pk_fma_f32 v[94:95], v[50:51], v[94:95], v[96:97]
	v_mul_f32_e32 v96, v93, v93
	v_pk_fma_f32 v[104:105], v[92:93], v[92:93], v[96:97] op_sel_hi:[1,1,0]
	v_mul_f32_e32 v96, v95, v95
	v_pk_fma_f32 v[110:111], v[94:95], v[94:95], v[96:97] op_sel_hi:[1,1,0]
	s_waitcnt vmcnt(6)
	v_mov_b32_e32 v98, v168
	v_mov_b32_e32 v99, v169
	v_mov_b32_e32 v112, v170
	v_mov_b32_e32 v113, v171
	v_lshlrev_b32_e32 v96, 16, v98
	v_and_b32_e32 v97, 0xffff0000, v98
	v_lshlrev_b32_e32 v98, 16, v99
	v_and_b32_e32 v99, 0xffff0000, v99
	v_pk_mul_f32 v[96:97], v[82:83], v[96:97] op_sel_hi:[0,1]
	v_lshlrev_b32_e32 v114, 16, v112
	v_and_b32_e32 v115, 0xffff0000, v112
	v_pk_mul_f32 v[98:99], v[82:83], v[98:99] op_sel_hi:[0,1]
	v_lshlrev_b32_e32 v112, 16, v113
	v_and_b32_e32 v113, 0xffff0000, v113
	v_pk_fma_f32 v[96:97], v[48:49], v[96:97], v[114:115]
	v_pk_fma_f32 v[98:99], v[46:47], v[98:99], v[112:113]
	v_pk_mul_f32 v[112:113], v[96:97], v[96:97]
	v_pk_mul_f32 v[114:115], v[98:99], v[98:99]
	v_mov_b32_e32 v101, v112
	v_mov_b32_e32 v103, v113
	v_mov_b32_e32 v105, v115
	v_mov_b32_e32 v111, v114
	v_pk_add_f32 v[100:101], v[100:101], v[102:103]
	v_pk_add_f32 v[102:103], v[104:105], v[110:111]
	v_pk_add_f32 v[100:101], v[100:101], v[102:103]
	s_waitcnt vmcnt(4)
; __device__ __forceinline__ float bflo(unsigned u) { return __uint_as_float(u << 16); }
; __device__ __forceinline__ float bfhi(unsigned u) { return __uint_as_float(u & 0xffff0000u); }
; __device__ __forceinline__ void phase_final(const bf16_t* h1, const bf16_t* d2, const float* rr, const float* g1, const float* gain, float* dst, int tid) {
;     ...
;         for (int j = 0; j < 8; ++j) { const u32x2 p = *(const u32x2*)(h1 + (size_t)row * DM + 4 * (lane + 64 * j)), q = *(const u32x2*)(d2 + (size_t)row * DM + 4 * (lane + 64 * j));
;             v[j][0] = bflo(p.x) * sc * ig[j][0] + bflo(q.x); v[j][1] = bfhi(p.x) * sc * ig[j][1] + bfhi(q.x); v[j][2] = bflo(p.y) * sc * ig[j][2] + bflo(q.y); v[j][3] = bfhi(p.y) * sc * ig[j][3] + bfhi(q.y);
;             ss += (v[j][0] * v[j][0] + v[j][1] * v[j][1]) + (v[j][2] * v[j][2] + v[j][3] * v[j][3]); }
;         const float r = rsqrtf(wave_sum(ss) * (1.f / DM) + EPSN);
; #pragma unroll
;         for (int j = 0; j < 8; ++j) __builtin_nontemporal_store(v[j] * r * gv[j], (f32x4*)(dst + (size_t)row * DM + 4 * (lane + 64 * j)));
	v_mov_b32_e32 v104, v172
	v_mov_b32_e32 v105, v173
	v_mov_b32_e32 v110, v174
	v_mov_b32_e32 v111, v175
	v_lshlrev_b32_e32 v102, 16, v104
	v_and_b32_e32 v103, 0xffff0000, v104
	v_lshlrev_b32_e32 v104, 16, v105
	v_and_b32_e32 v105, 0xffff0000, v105
	v_pk_mul_f32 v[102:103], v[82:83], v[102:103] op_sel_hi:[0,1]
	v_lshlrev_b32_e32 v112, 16, v110
	v_and_b32_e32 v113, 0xffff0000, v110
	v_pk_mul_f32 v[104:105], v[82:83], v[104:105] op_sel_hi:[0,1]
	v_lshlrev_b32_e32 v110, 16, v111
	v_and_b32_e32 v111, 0xffff0000, v111
	v_pk_fma_f32 v[102:103], v[44:45], v[102:103], v[112:113]
	v_pk_fma_f32 v[104:105], v[42:43], v[104:105], v[110:111]
	v_mov_b32_e32 v112, v102
	v_pk_mov_b32 v[110:111], v[102:103], v[104:105] op_sel:[1,0]
	v_mov_b32_e32 v113, v105
	v_pk_mul_f32 v[110:111], v[110:111], v[110:111]
	v_pk_add_f32 v[100:101], v[100:101], v[100:101] op_sel:[0,1] op_sel_hi:[1,0]
	v_pk_fma_f32 v[110:111], v[112:113], v[112:113], v[110:111]
	s_nop 0
	v_pk_add_f32 v[114:115], v[110:111], v[110:111] op_sel:[0,1] op_sel_hi:[1,0]
	s_waitcnt vmcnt(0)
	v_mov_b32_e32 v112, v190
	v_mov_b32_e32 v113, v191
	v_mov_b32_e32 v116, v192
	v_mov_b32_e32 v117, v193
	v_mov_b32_e32 v120, v194
	v_mov_b32_e32 v121, v195
	v_mov_b32_e32 v106, v196
	v_mov_b32_e32 v107, v197
	v_lshlrev_b32_e32 v110, 16, v112
	v_and_b32_e32 v111, 0xffff0000, v112
	v_lshlrev_b32_e32 v112, 16, v113
	v_and_b32_e32 v113, 0xffff0000, v113
	v_pk_mul_f32 v[110:111], v[82:83], v[110:111] op_sel_hi:[0,1]
	v_lshlrev_b32_e32 v118, 16, v116
	v_and_b32_e32 v119, 0xffff0000, v116
	v_pk_mul_f32 v[112:113], v[82:83], v[112:113] op_sel_hi:[0,1]
	v_lshlrev_b32_e32 v116, 16, v117
	v_and_b32_e32 v117, 0xffff0000, v117
	v_lshlrev_b32_e32 v108, 16, v120
	v_and_b32_e32 v109, 0xffff0000, v120
	v_lshlrev_b32_e32 v120, 16, v121
	v_and_b32_e32 v121, 0xffff0000, v121
	v_pk_fma_f32 v[110:111], v[40:41], v[110:111], v[118:119]
	v_pk_fma_f32 v[112:113], v[38:39], v[112:113], v[116:117]
	v_pk_mul_f32 v[108:109], v[82:83], v[108:109] op_sel_hi:[0,1]
	v_lshlrev_b32_e32 v152, 16, v106
	v_and_b32_e32 v153, 0xffff0000, v106
	v_pk_mul_f32 v[120:121], v[82:83], v[120:121] op_sel_hi:[0,1]
	v_lshlrev_b32_e32 v106, 16, v107
	v_and_b32_e32 v107, 0xffff0000, v107
	v_mul_f32_e32 v116, v111, v111
	v_mul_f32_e32 v118, v113, v113
	v_pk_fma_f32 v[108:109], v[36:37], v[108:109], v[152:153]
	v_pk_fma_f32 v[106:107], v[34:35], v[120:121], v[106:107]
	v_pk_fma_f32 v[116:117], v[110:111], v[110:111], v[116:117] op_sel_hi:[1,1,0]
	v_pk_fma_f32 v[118:119], v[112:113], v[112:113], v[118:119] op_sel_hi:[1,1,0]
	v_pk_mul_f32 v[120:121], v[108:109], v[108:109]
	v_pk_mul_f32 v[152:153], v[106:107], v[106:107]
	v_mov_b32_e32 v101, v120
	v_mov_b32_e32 v115, v121
	v_mov_b32_e32 v117, v153
	v_mov_b32_e32 v119, v152
	v_pk_add_f32 v[100:101], v[100:101], v[114:115]
	v_pk_add_f32 v[114:115], v[116:117], v[118:119]
	s_nop 0
	v_pk_add_f32 v[100:101], v[100:101], v[114:115]
	s_nop 0
	v_add_f32_e32 v71, v100, v101
	ds_bpermute_b32 v73, v83, v71
	v_lshlrev_b64 v[100:101], 13, v[32:33]
	v_lshl_add_u64 v[100:101], s[14:15], 0, v[100:101]
	v_lshl_add_u64 v[114:115], v[100:101], 0, v[136:137]
	v_add_u32_e32 v32, s99, v32
	s_waitcnt lgkmcnt(0)
	v_add_f32_e32 v71, v71, v73
	ds_bpermute_b32 v73, v122, v71
	s_waitcnt lgkmcnt(0)
	v_add_f32_e32 v71, v71, v73
	ds_bpermute_b32 v73, v123, v71
	s_waitcnt lgkmcnt(0)
	v_add_f32_e32 v71, v71, v73
	ds_bpermute_b32 v73, v124, v71
	s_waitcnt lgkmcnt(0)
	v_add_f32_e32 v71, v71, v73
	ds_bpermute_b32 v73, v125, v71
	s_waitcnt lgkmcnt(0)
	v_add_f32_e32 v71, v71, v73
	ds_bpermute_b32 v73, v126, v71
	s_waitcnt lgkmcnt(0)
	v_add_f32_e32 v71, v71, v73
	v_fmamk_f32 v71, v71, 0x3a000000, v181
	v_cmp_gt_f32_e32 vcc, s77, v71
	v_mul_f32_e32 v73, 0x4b800000, v71
	s_nop 0
	v_cndmask_b32_e32 v71, v71, v73, vcc
	v_rsq_f32_e32 v71, v71
	s_nop 0
	v_mul_f32_e32 v73, 0x45800000, v71
	v_cndmask_b32_e32 v82, v71, v73, vcc
	v_pk_mul_f32 v[78:79], v[78:79], v[82:83] op_sel_hi:[1,0]
	v_pk_mul_f32 v[80:81], v[80:81], v[82:83] op_sel_hi:[1,0]
	v_pk_mul_f32 v[78:79], v[0:1], v[78:79]
	v_pk_mul_f32 v[80:81], v[2:3], v[80:81]
	global_store_dwordx4 v[114:115], v[78:81], off nt
	v_mov_b32_e32 v71, v137
	v_mov_b32_e32 v73, v137
	v_pk_mul_f32 v[78:79], v[84:85], v[82:83] op_sel_hi:[1,0]
	v_pk_mul_f32 v[80:81], v[86:87], v[82:83] op_sel_hi:[1,0]
	v_pk_mul_f32 v[78:79], v[4:5], v[78:79]
	v_pk_mul_f32 v[80:81], v[6:7], v[80:81]
	global_store_dwordx4 v[114:115], v[78:81], off offset:1024 nt
	v_lshl_add_u64 v[84:85], v[100:101], 0, v[70:71]
	v_cmp_lt_i32_e32 vcc, s81, v32
	v_pk_mul_f32 v[78:79], v[88:89], v[82:83] op_sel_hi:[1,0]
	v_pk_mul_f32 v[80:81], v[90:91], v[82:83] op_sel_hi:[1,0]
	v_pk_mul_f32 v[78:79], v[8:9], v[78:79]
	v_pk_mul_f32 v[80:81], v[10:11], v[80:81]
	global_store_dwordx4 v[114:115], v[78:81], off offset:2048 nt
	s_or_b64 s[16:17], vcc, s[16:17]
	s_nop 0
	v_pk_mul_f32 v[78:79], v[92:93], v[82:83] op_sel_hi:[1,0]
	v_pk_mul_f32 v[80:81], v[94:95], v[82:83] op_sel_hi:[1,0]
	v_pk_mul_f32 v[78:79], v[12:13], v[78:79]
	v_pk_mul_f32 v[80:81], v[14:15], v[80:81]
	global_store_dwordx4 v[114:115], v[78:81], off offset:3072 nt
	s_nop 1
	v_pk_mul_f32 v[78:79], v[96:97], v[82:83] op_sel_hi:[1,0]
	v_pk_mul_f32 v[80:81], v[98:99], v[82:83] op_sel_hi:[1,0]
	v_pk_mul_f32 v[78:79], v[16:17], v[78:79]
	v_pk_mul_f32 v[80:81], v[18:19], v[80:81]
	global_store_dwordx4 v[84:85], v[78:81], off nt
	v_lshl_add_u64 v[84:85], v[100:101], 0, v[72:73]
	s_nop 0
	v_pk_mul_f32 v[78:79], v[102:103], v[82:83] op_sel_hi:[1,0]
	v_pk_mul_f32 v[80:81], v[104:105], v[82:83] op_sel_hi:[1,0]
	v_pk_mul_f32 v[78:79], v[20:21], v[78:79]
	v_pk_mul_f32 v[80:81], v[22:23], v[80:81]
	global_store_dwordx4 v[84:85], v[78:81], off nt
	v_lshl_add_u64 v[84:85], v[100:101], 0, v[74:75]
	s_nop 0
	v_pk_mul_f32 v[78:79], v[110:111], v[82:83] op_sel_hi:[1,0]
	v_pk_mul_f32 v[80:81], v[112:113], v[82:83] op_sel_hi:[1,0]
	v_pk_mul_f32 v[78:79], v[24:25], v[78:79]
	v_pk_mul_f32 v[80:81], v[26:27], v[80:81]
	global_store_dwordx4 v[84:85], v[78:81], off nt
	v_lshl_add_u64 v[84:85], v[100:101], 0, v[76:77]
	s_nop 0
	v_pk_mul_f32 v[78:79], v[108:109], v[82:83] op_sel_hi:[1,0]
	v_pk_mul_f32 v[80:81], v[106:107], v[82:83] op_sel_hi:[1,0]
	v_pk_mul_f32 v[78:79], v[28:29], v[78:79]
	v_pk_mul_f32 v[80:81], v[30:31], v[80:81]
	global_store_dwordx4 v[84:85], v[78:81], off nt
	s_andn2_b64 exec, exec, s[16:17]
	s_cbranch_execnz .LBB0_228

; __device__ __forceinline__ float bflo(unsigned u) { return __uint_as_float(u << 16); }
; __device__ __forceinline__ float bfhi(unsigned u) { return __uint_as_float(u & 0xffff0000u); }
; template <bool FINAL>
; __device__ __forceinline__ void norm_row(int row, const float* src, const bf16_t* d1, const bf16_t* d2, const f32x4 (&gv)[8], bf16_t* dsth, float* dstf, int lane, bf16_t* xb = nullptr) {
;     const float* xr = src + (size_t)row * DM;
;     f32x4 v[8]; float ss = 0.f;
; #pragma unroll
;     for (int j = 0; j < 8; ++j) v[j] = *(const f32x4*)(xr + 4 * (lane + 64 * j));
;     if (d1) {
; #pragma unroll
;         for (int j = 0; j < 8; ++j) { const u32x2 a = *(const u32x2*)(d1 + (size_t)row * DM + 4 * (lane + 64 * j));
;             v[j][0] += bflo(a.x); v[j][1] += bfhi(a.x); v[j][2] += bflo(a.y); v[j][3] += bfhi(a.y); } }
;     if (d2) {
; #pragma unroll
;         for (int j = 0; j < 8; ++j) { const u32x2 a = *(const u32x2*)(d2 + (size_t)row * DM + 4 * (lane + 64 * j));
;             v[j][0] += bflo(a.x); v[j][1] += bfhi(a.x); v[j][2] += bflo(a.y); v[j][3] += bfhi(a.y); } }
; #pragma unroll
;     for (int j = 0; j < 8; ++j) ss += (v[j][0] * v[j][0] + v[j][1] * v[j][1]) + (v[j][2] * v[j][2] + v[j][3] * v[j][3]);
;     const float msq = wave_sum(ss) * (1.f / DM) + EPSN, r = rsqrtf(msq);
;     if (xb && lane == 0) ((float*)xb)[row] = sqrtf(msq);
.LBB0_234:
	v_ashrrev_i32_e32 v45, 31, v44
	v_lshlrev_b64 v[32:33], 13, v[44:45]
	v_lshl_add_u64 v[32:33], s[6:7], 0, v[32:33]
	v_lshlrev_b64 v[78:79], 12, v[44:45]
	v_lshl_add_u64 v[34:35], v[32:33], 0, v[136:137]
	v_lshl_add_u64 v[78:79], v[46:47], 0, v[78:79]
	global_load_dwordx4 v[58:61], v[34:35], off
	global_load_dwordx4 v[62:65], v[34:35], off offset:1024
	global_load_dwordx4 v[66:69], v[34:35], off offset:2048
	global_load_dwordx4 v[70:73], v[34:35], off offset:3072
	global_load_dwordx2 v[86:87], v[78:79], off
	v_mov_b32_e32 v51, v137
	v_lshl_add_u64 v[34:35], v[32:33], 0, v[50:51]
	global_load_dwordx4 v[74:77], v[34:35], off
	v_mov_b32_e32 v53, v137
	v_lshl_add_u64 v[34:35], v[32:33], 0, v[52:53]
	global_load_dwordx4 v[40:43], v[34:35], off
	v_mov_b32_e32 v55, v137
	v_lshl_add_u64 v[34:35], v[32:33], 0, v[54:55]
	v_mov_b32_e32 v57, v137
	global_load_dwordx4 v[36:39], v[34:35], off
	v_lshl_add_u64 v[32:33], v[32:33], 0, v[56:57]
	global_load_dwordx4 v[32:35], v[32:33], off
	global_load_dwordx2 v[156:157], v[78:79], off offset:512
	global_load_dwordx2 v[158:159], v[78:79], off offset:1024
	global_load_dwordx2 v[160:161], v[78:79], off offset:1536
	global_load_dwordx2 v[162:163], v[78:79], off offset:2048
	global_load_dwordx2 v[164:165], v[78:79], off offset:2560
	global_load_dwordx2 v[166:167], v[78:79], off offset:3072
	global_load_dwordx2 v[168:169], v[78:79], off offset:3584
	s_waitcnt vmcnt(7)
	v_lshlrev_b32_e32 v88, 16, v86
	v_and_b32_e32 v89, 0xffff0000, v86
	v_lshlrev_b32_e32 v86, 16, v87
	v_and_b32_e32 v87, 0xffff0000, v87
	v_pk_add_f32 v[60:61], v[60:61], v[86:87]
	v_pk_add_f32 v[58:59], v[58:59], v[88:89]
	s_waitcnt vmcnt(6)
	v_mov_b32_e32 v86, v156
	v_mov_b32_e32 v87, v157
	v_lshlrev_b32_e32 v88, 16, v86
	v_and_b32_e32 v89, 0xffff0000, v86
	v_lshlrev_b32_e32 v86, 16, v87
	v_and_b32_e32 v87, 0xffff0000, v87
	v_pk_add_f32 v[64:65], v[64:65], v[86:87]
	v_pk_add_f32 v[62:63], v[62:63], v[88:89]
	v_pk_mul_f32 v[90:91], v[64:65], v[64:65]
	s_waitcnt vmcnt(5)
	v_mov_b32_e32 v86, v158
	v_mov_b32_e32 v87, v159
	v_lshlrev_b32_e32 v88, 16, v86
	v_and_b32_e32 v89, 0xffff0000, v86
	v_lshlrev_b32_e32 v86, 16, v87
	v_and_b32_e32 v87, 0xffff0000, v87
	v_pk_add_f32 v[68:69], v[68:69], v[86:87]
	v_pk_add_f32 v[66:67], v[66:67], v[88:89]
	v_add_f32_e32 v51, v90, v91
	v_pk_mul_f32 v[92:93], v[66:67], v[66:67]
	v_pk_mul_f32 v[94:95], v[68:69], v[68:69]
	s_waitcnt vmcnt(4)
	v_mov_b32_e32 v86, v160
	v_mov_b32_e32 v87, v161
	v_lshlrev_b32_e32 v88, 16, v86
	v_and_b32_e32 v89, 0xffff0000, v86
	v_lshlrev_b32_e32 v86, 16, v87
	v_and_b32_e32 v87, 0xffff0000, v87
	v_pk_add_f32 v[72:73], v[72:73], v[86:87]
	v_pk_add_f32 v[70:71], v[70:71], v[88:89]
	v_pk_mul_f32 v[98:99], v[72:73], v[72:73]
	v_pk_mul_f32 v[96:97], v[70:71], v[70:71]
	s_waitcnt vmcnt(3)
	v_mov_b32_e32 v86, v162
	v_mov_b32_e32 v87, v163
	v_lshlrev_b32_e32 v88, 16, v86
	v_and_b32_e32 v89, 0xffff0000, v86
	v_lshlrev_b32_e32 v86, 16, v87
	v_and_b32_e32 v87, 0xffff0000, v87
	v_pk_add_f32 v[76:77], v[76:77], v[86:87]
	v_pk_add_f32 v[74:75], v[74:75], v[88:89]
	v_pk_mul_f32 v[102:103], v[76:77], v[76:77]
	v_pk_mul_f32 v[100:101], v[74:75], v[74:75]
	s_waitcnt vmcnt(2)
	v_mov_b32_e32 v86, v164
	v_mov_b32_e32 v87, v165
	v_lshlrev_b32_e32 v88, 16, v86
	v_and_b32_e32 v89, 0xffff0000, v86
	v_lshlrev_b32_e32 v86, 16, v87
	v_and_b32_e32 v87, 0xffff0000, v87
	v_pk_add_f32 v[42:43], v[42:43], v[86:87]
	v_pk_add_f32 v[40:41], v[40:41], v[88:89]
	v_pk_mul_f32 v[104:105], v[40:41], v[40:41]
	v_pk_mul_f32 v[106:107], v[42:43], v[42:43]
	s_waitcnt vmcnt(0)
	v_mov_b32_e32 v86, v166
	v_mov_b32_e32 v87, v167
	v_mov_b32_e32 v78, v168
	v_mov_b32_e32 v79, v169
	v_lshlrev_b32_e32 v88, 16, v86
	v_and_b32_e32 v89, 0xffff0000, v86
	v_lshlrev_b32_e32 v86, 16, v87
	v_and_b32_e32 v87, 0xffff0000, v87
	v_pk_add_f32 v[36:37], v[36:37], v[88:89]
	v_pk_add_f32 v[38:39], v[38:39], v[86:87]
	v_lshlrev_b32_e32 v86, 16, v78
	v_and_b32_e32 v87, 0xffff0000, v78
	v_lshlrev_b32_e32 v78, 16, v79
	v_and_b32_e32 v79, 0xffff0000, v79
	v_pk_mul_f32 v[88:89], v[62:63], v[62:63]
	v_pk_add_f32 v[32:33], v[32:33], v[86:87]
	v_pk_add_f32 v[34:35], v[34:35], v[78:79]
	v_pk_mul_f32 v[78:79], v[58:59], v[58:59]
	v_pk_mul_f32 v[86:87], v[60:61], v[60:61]
	v_add_f32_e32 v53, v88, v89
	v_add_f32_e32 v51, v53, v51
	v_add_f32_e32 v53, v86, v87
	v_add_f32_e32 v55, v78, v79
	v_add_f32_e32 v53, v55, v53
	v_add_f32_e32 v51, v53, v51
	v_add_f32_e32 v53, v94, v95
	v_add_f32_e32 v55, v92, v93
	v_add_f32_e32 v53, v55, v53
	v_add_f32_e32 v51, v53, v51
	v_add_f32_e32 v53, v98, v99
	v_add_f32_e32 v55, v96, v97
	v_add_f32_e32 v53, v55, v53
	v_add_f32_e32 v51, v53, v51
	v_add_f32_e32 v53, v102, v103
	v_add_f32_e32 v55, v100, v101
	v_add_f32_e32 v53, v55, v53
	v_add_f32_e32 v51, v53, v51
	v_add_f32_e32 v53, v106, v107
	v_add_f32_e32 v55, v104, v105
	v_pk_mul_f32 v[108:109], v[36:37], v[36:37]
	v_pk_mul_f32 v[110:111], v[38:39], v[38:39]
	v_add_f32_e32 v53, v55, v53
	v_add_f32_e32 v51, v53, v51
	v_add_f32_e32 v53, v110, v111
	v_add_f32_e32 v55, v108, v109
	v_pk_mul_f32 v[112:113], v[32:33], v[32:33]
	v_pk_mul_f32 v[114:115], v[34:35], v[34:35]
	v_add_f32_e32 v53, v55, v53
	v_add_f32_e32 v51, v53, v51
	v_add_f32_e32 v53, v114, v115
	v_add_f32_e32 v55, v112, v113
	v_add_f32_e32 v53, v55, v53
	v_add_f32_e32 v51, v53, v51
	ds_bpermute_b32 v53, v80, v51
	s_waitcnt lgkmcnt(0)
	v_add_f32_e32 v51, v51, v53
	ds_bpermute_b32 v53, v81, v51
	s_waitcnt lgkmcnt(0)
	v_add_f32_e32 v51, v51, v53
	ds_bpermute_b32 v53, v82, v51
	s_waitcnt lgkmcnt(0)
	v_add_f32_e32 v51, v51, v53
	ds_bpermute_b32 v53, v83, v51
	s_waitcnt lgkmcnt(0)
	v_add_f32_e32 v51, v51, v53
	ds_bpermute_b32 v53, v84, v51
	s_waitcnt lgkmcnt(0)
	v_add_f32_e32 v51, v51, v53
	ds_bpermute_b32 v53, v85, v51
	s_waitcnt lgkmcnt(0)
	v_add_f32_e32 v51, v51, v53
	v_fmamk_f32 v51, v51, 0x3a000000, v181
	s_and_saveexec_b64 s[18:19], vcc
	s_cbranch_execz .LBB0_233
	s_mov_b32 s0, 0xf800000
	v_mul_f32_e32 v53, 0x4f800000, v51
	v_cmp_gt_f32_e64 s[0:1], s0, v51
	v_lshl_add_u64 v[78:79], v[44:45], 2, s[12:13]
	s_nop 0
	v_cndmask_b32_e64 v53, v51, v53, s[0:1]
	v_sqrt_f32_e32 v55, v53
	s_nop 0
	v_add_u32_e32 v57, -1, v55
	v_fma_f32 v86, -v57, v55, v53
	v_cmp_ge_f32_e64 s[40:41], 0, v86
	v_add_u32_e32 v86, 1, v55
	s_nop 0
	v_cndmask_b32_e64 v57, v55, v57, s[40:41]
	v_fma_f32 v55, -v86, v55, v53
	v_cmp_lt_f32_e64 s[40:41], 0, v55
	s_nop 1
	v_cndmask_b32_e64 v55, v57, v86, s[40:41]
	v_mul_f32_e32 v57, 0x37800000, v55
	v_cndmask_b32_e64 v55, v55, v57, s[0:1]
	v_cmp_class_f32_e64 s[0:1], v53, v182
	s_nop 1
	v_cndmask_b32_e64 v53, v55, v53, s[0:1]
	global_store_dword v[78:79], v53, off
	s_branch .LBB0_233
